# nt cache hints on more read-once streams: LN y loads, modulate x loads, f32 weight loads in conversion loops, mod_w loads
# speedup vs baseline: 1.0193x; 1.0013x over previous
; DI void mod_phase(const Args& a, float* ldsf) {
;     ...
;         for (int k0 = ks * 128; k0 < ks * 128 + 128; k0 += 16) {
;             float w[16];
; #pragma unroll
;             for (int u = 0; u < 16; ++u) w[u] = W[(size_t)(k0 + u) * 3072];
; #pragma unroll
;             for (int u = 0; u < 16; ++u) {
; #pragma unroll
;                 for (int bb = 0; bb < 9; ++bb) acc[bb] = fmaf(ldsf[bb * 1024 + k0 + u], w[u], acc[bb]); } }
.LBB0_21:
	v_add_co_u32_e32 v106, vcc, 0xfffd3000, v84
	v_add_u32_e32 v95, 0x101c, v122
	s_nop 0
	v_addc_co_u32_e32 v107, vcc, -1, v85, vcc
	v_add_u32_e32 v131, 0x601c, v122
	v_add_u32_e32 v144, 0x701c, v122
	v_add_u32_e32 v146, 0x1024, v122
	v_add_u32_e32 v148, 0x2024, v122
	v_add_u32_e32 v150, 0x3024, v122
	v_add_u32_e32 v152, 0x4024, v122
	v_add_u32_e32 v154, 0x5024, v122
	v_add_u32_e32 v158, 0x6024, v122
	v_add_u32_e32 v160, 0x7024, v122
	v_add_u32_e32 v156, 0x202c, v122
	v_add_u32_e32 v162, 0x102c, v122
	v_add_u32_e32 v164, 0x302c, v122
	v_add_u32_e32 v166, 0x402c, v122
	v_add_u32_e32 v168, 0x502c, v122
	v_add_u32_e32 v170, 0x602c, v122
	v_add_u32_e32 v176, 0x702c, v122
	v_add_u32_e32 v172, 0x4034, v122
	v_add_u32_e32 v174, 0x6034, v122
	v_add_u32_e32 v178, 0x2034, v122
	v_add_co_u32_e32 v130, vcc, 0xfffd6000, v84
	ds_read_b128 v[6:9], v122
	ds_read_b96 v[46:48], v122 offset:16
	ds_read_b128 v[2:5], v122 offset:12288
	ds_read_b32 v94, v122 offset:8252
	ds_read_b128 v[10:13], v122 offset:20480
	ds_read_b32 v96, v122 offset:16444
	ds_read_b128 v[14:17], v122 offset:28672
	ds_read_b32 v98, v122 offset:24636
	ds_read_b128 v[22:25], v122 offset:32768
	ds_read_b128 v[18:21], v122 offset:32784
	ds_read_b128 v[30:33], v122 offset:8192
	ds_read_b96 v[70:72], v122 offset:8208
	ds_read_b128 v[34:37], v122 offset:16384
	ds_read_b96 v[66:68], v122 offset:16400
	ds_read_b96 v[50:52], v122 offset:4112
	ds_read_b32 v49, v122 offset:4148
	ds_read_b64 v[104:105], v122 offset:4152
	ds_read_b96 v[54:56], v122 offset:12304
	ds_read_b32 v53, v122 offset:12340
	ds_read_b64 v[100:101], v122 offset:12344
	ds_read_b32 v57, v122 offset:20532
	ds_read_b64 v[102:103], v122 offset:20536
	ds_read_b96 v[58:60], v122 offset:20496
	ds_read_b128 v[42:45], v122 offset:24576
	ds_read_b96 v[74:76], v122 offset:24592
	ds_read_b96 v[62:64], v122 offset:28688
	ds_read_b32 v61, v122 offset:28724
	ds_read_b64 v[108:109], v122 offset:28728
	v_add_u32_e32 v97, 0x201c, v122
	v_add_u32_e32 v99, 0x301c, v122
	v_add_u32_e32 v119, 0x401c, v122
	v_add_u32_e32 v125, 0x501c, v122
	ds_read2_b32 v[114:115], v122 offset0:7 offset1:8
	ds_read2_b32 v[116:117], v122 offset0:9 offset1:10
	ds_read2_b32 v[110:111], v122 offset0:11 offset1:12
	ds_read2_b32 v[120:121], v122 offset0:13 offset1:14
	ds_read_b128 v[38:41], v122 offset:32800
	ds_read_b128 v[26:29], v122 offset:32816
	global_load_dword v112, v[84:85], off nt
	ds_read_b128 v[126:129], v122 offset:4096
	ds_read_b32 v118, v122 offset:60
	ds_read2_b32 v[132:133], v95 offset1:1
	ds_read2_b32 v[134:135], v97 offset1:1
	ds_read2_b32 v[136:137], v99 offset1:1
	ds_read2_b32 v[138:139], v119 offset1:1
	ds_read2_b32 v[140:141], v125 offset1:1
	ds_read2_b32 v[142:143], v131 offset1:1
	ds_read2_b32 v[144:145], v144 offset1:1
	ds_read2_b32 v[146:147], v146 offset1:1
	ds_read2_b32 v[148:149], v148 offset1:1
	ds_read2_b32 v[150:151], v150 offset1:1
	ds_read2_b32 v[152:153], v152 offset1:1
	ds_read2_b32 v[154:155], v154 offset1:1
	ds_read2_b32 v[156:157], v156 offset1:1
	ds_read2_b32 v[158:159], v158 offset1:1
	ds_read2_b32 v[160:161], v160 offset1:1
	ds_read2_b32 v[162:163], v162 offset1:1
	ds_read2_b32 v[164:165], v164 offset1:1
	ds_read2_b32 v[166:167], v166 offset1:1
	ds_read2_b32 v[168:169], v168 offset1:1
	ds_read2_b32 v[170:171], v170 offset1:1
	ds_read2_b32 v[172:173], v172 offset1:1
	ds_read2_b32 v[174:175], v174 offset1:1
	ds_read2_b32 v[176:177], v176 offset1:1
	ds_read2_b32 v[178:179], v178 offset1:1
	v_addc_co_u32_e32 v131, vcc, -1, v85, vcc
	v_add_co_u32_e32 v180, vcc, 0xfffd9000, v84
	global_load_dword v106, v[106:107], off nt
	s_nop 0
	v_addc_co_u32_e32 v181, vcc, -1, v85, vcc
	v_add_co_u32_e32 v182, vcc, 0xfffdc000, v84
	global_load_dword v130, v[130:131], off nt
	s_nop 0
	global_load_dword v180, v[180:181], off nt
	v_addc_co_u32_e32 v183, vcc, -1, v85, vcc
	v_add_co_u32_e32 v184, vcc, 0xfffdf000, v84
	s_waitcnt lgkmcnt(14)
	v_mov_b32_e32 v186, v6
	v_addc_co_u32_e32 v185, vcc, -1, v85, vcc
	v_mov_b32_e32 v6, v8
	v_mov_b32_e32 v8, v30
	v_mov_b32_e32 v30, v32
	v_mov_b32_e32 v32, v34
	v_mov_b32_e32 v34, v36
	v_mov_b32_e32 v36, v42
	v_mov_b32_e32 v42, v44
	global_load_dword v44, v[182:183], off nt
	v_add_co_u32_e32 v182, vcc, 0xfffe2000, v84
	v_mov_b32_e32 v188, v46
	s_nop 0
	v_addc_co_u32_e32 v183, vcc, -1, v85, vcc
	v_mov_b32_e32 v46, v48
	v_mov_b32_e32 v48, v120
	v_pk_mov_b32 v[120:121], v[120:121], v[104:105] op_sel:[1,0]
	v_add_co_u32_e32 v104, vcc, 0xfffe5000, v84
	v_mov_b32_e32 v119, v105
	s_nop 0
	v_addc_co_u32_e32 v105, vcc, -1, v85, vcc
	v_mov_b32_e32 v196, v114
	v_mov_b32_e32 v114, v116
	v_mov_b32_e32 v116, v110
	v_add_co_u32_e32 v110, vcc, 0xfffe8000, v84
	v_mov_b32_e32 v197, v132
	v_mov_b32_e32 v132, v115
	v_mov_b32_e32 v115, v146
	v_mov_b32_e32 v146, v117
	s_waitcnt lgkmcnt(8)
	v_mov_b32_e32 v117, v162
	v_mov_b32_e32 v162, v111
	v_addc_co_u32_e32 v111, vcc, -1, v85, vcc
	v_mov_b32_e32 v198, v134
	v_mov_b32_e32 v134, v148
	v_mov_b32_e32 v148, v156
	v_add_co_u32_e32 v156, vcc, 0xfffeb000, v84
	v_mov_b32_e32 v199, v136
	v_mov_b32_e32 v136, v135
	v_mov_b32_e32 v135, v150
	v_mov_b32_e32 v150, v149
	s_waitcnt lgkmcnt(7)
	v_mov_b32_e32 v149, v164
	v_mov_b32_e32 v164, v157
	v_addc_co_u32_e32 v157, vcc, -1, v85, vcc
	v_mov_b32_e32 v190, v70
	v_mov_b32_e32 v192, v66
	v_mov_b32_e32 v70, v72
	v_mov_b32_e32 v66, v68
	v_mov_b32_e32 v194, v74
	v_mov_b32_e32 v195, v62
	v_mov_b32_e32 v62, v75
	v_mov_b32_e32 v74, v76
	v_mov_b32_e32 v75, v64
	global_load_dword v64, v[184:185], off nt
	global_load_dword v68, v[182:183], off nt
	global_load_dword v72, v[104:105], off nt
	global_load_dword v76, v[110:111], off nt
	v_add_co_u32_e32 v104, vcc, 0xfffee000, v84
	v_mov_b32_e32 v200, v138
	s_nop 0
	v_addc_co_u32_e32 v105, vcc, -1, v85, vcc
	v_add_co_u32_e32 v110, vcc, 0xffff1000, v84
	v_mov_b32_e32 v138, v152
	s_nop 0
	v_addc_co_u32_e32 v111, vcc, -1, v85, vcc
	s_waitcnt lgkmcnt(6)
; DI void mod_phase(const Args& a, float* ldsf) {
;     ...
;             for (int u = 0; u < 16; ++u) w[u] = W[(size_t)(k0 + u) * 3072];
; #pragma unroll
;             for (int u = 0; u < 16; ++u) {
; #pragma unroll
;                 for (int bb = 0; bb < 9; ++bb) acc[bb] = fmaf(ldsf[bb * 1024 + k0 + u], w[u], acc[bb]); } }
	v_mov_b32_e32 v152, v166
	v_add_co_u32_e32 v166, vcc, 0xffff4000, v84
	v_mov_b32_e32 v201, v140
	v_mov_b32_e32 v140, v139
	v_mov_b32_e32 v139, v154
	v_mov_b32_e32 v154, v153
	s_waitcnt lgkmcnt(5)
	v_mov_b32_e32 v153, v168
	v_mov_b32_e32 v168, v167
	v_addc_co_u32_e32 v167, vcc, -1, v85, vcc
	v_mov_b32_e32 v202, v142
	v_mov_b32_e32 v142, v158
	s_waitcnt lgkmcnt(4)
	v_mov_b32_e32 v158, v170
	v_add_co_u32_e32 v170, vcc, 0xffff7000, v84
	v_mov_b32_e32 v203, v144
	v_mov_b32_e32 v144, v143
	v_mov_b32_e32 v143, v160
	v_mov_b32_e32 v160, v159
	s_waitcnt lgkmcnt(1)
	v_mov_b32_e32 v159, v176
	v_mov_b32_e32 v176, v171
	global_load_dword v156, v[156:157], off nt
	s_nop 0
	global_load_dword v104, v[104:105], off nt
	v_addc_co_u32_e32 v171, vcc, -1, v85, vcc
	v_mov_b32_e32 v191, v54
	v_mov_b32_e32 v54, v71
	v_mov_b32_e32 v71, v56
	v_mov_b32_e32 v97, v103
	v_mov_b32_e32 v56, v172
	v_pk_mov_b32 v[102:103], v[172:173], v[102:103] op_sel:[1,0]
	global_load_dword v110, v[110:111], off nt
	v_add_co_u32_e32 v172, vcc, 0xffffa000, v84
	global_load_dword v166, v[166:167], off nt
	s_nop 0
	v_addc_co_u32_e32 v173, vcc, -1, v85, vcc
	v_mov_b32_e32 v193, v58
	v_mov_b32_e32 v58, v67
	v_mov_b32_e32 v67, v60
	v_mov_b32_e32 v99, v109
	v_mov_b32_e32 v60, v174
	v_pk_mov_b32 v[108:109], v[174:175], v[108:109] op_sel:[1,0]
	global_load_dword v170, v[170:171], off nt
	v_add_co_u32_e32 v174, vcc, 0xffffd000, v84
	global_load_dword v172, v[172:173], off nt
	s_nop 0
	v_addc_co_u32_e32 v175, vcc, -1, v85, vcc
	global_load_dword v174, v[174:175], off nt
	v_mov_b32_e32 v187, v126
	v_mov_b32_e32 v126, v7
	v_mov_b32_e32 v7, v128
	v_mov_b32_e32 v128, v9
	v_mov_b32_e32 v9, v2
	v_mov_b32_e32 v2, v31
	v_mov_b32_e32 v31, v4
	v_mov_b32_e32 v4, v33
	v_mov_b32_e32 v33, v10
	v_mov_b32_e32 v10, v35
	v_mov_b32_e32 v35, v12
	v_mov_b32_e32 v12, v37
	v_mov_b32_e32 v37, v14
	v_mov_b32_e32 v14, v43
	s_waitcnt vmcnt(14)
	v_pk_fma_f32 v[86:87], v[186:187], v[106:107], v[86:87] op_sel_hi:[1,0,1]
	v_pk_fma_f32 v[8:9], v[8:9], v[106:107], v[88:89] op_sel_hi:[1,0,1]
	v_pk_fma_f32 v[32:33], v[32:33], v[106:107], v[90:91] op_sel_hi:[1,0,1]
	v_pk_fma_f32 v[36:37], v[36:37], v[106:107], v[92:93] op_sel_hi:[1,0,1]
	v_fmac_f32_e32 v124, v22, v106
	v_mov_b32_e32 v43, v16
	s_waitcnt vmcnt(13)
	v_fmac_f32_e32 v124, v23, v130
	v_pk_fma_f32 v[22:23], v[126:127], v[130:131], v[86:87] op_sel_hi:[1,0,1]
	v_pk_fma_f32 v[2:3], v[2:3], v[130:131], v[8:9] op_sel_hi:[1,0,1]
	v_pk_fma_f32 v[8:9], v[10:11], v[130:131], v[32:33] op_sel_hi:[1,0,1]
	v_pk_fma_f32 v[10:11], v[14:15], v[130:131], v[36:37] op_sel_hi:[1,0,1]
	v_mov_b32_e32 v16, v45
	s_waitcnt vmcnt(12)
	v_pk_fma_f32 v[6:7], v[6:7], v[180:181], v[22:23] op_sel_hi:[1,0,1]
	v_pk_fma_f32 v[2:3], v[30:31], v[180:181], v[2:3] op_sel_hi:[1,0,1]
	v_pk_fma_f32 v[8:9], v[34:35], v[180:181], v[8:9] op_sel_hi:[1,0,1]
	v_pk_fma_f32 v[10:11], v[42:43], v[180:181], v[10:11] op_sel_hi:[1,0,1]
	v_fmac_f32_e32 v124, v24, v180
	v_mov_b32_e32 v189, v50
	s_waitcnt vmcnt(11)
	v_fmac_f32_e32 v124, v25, v44
	v_pk_fma_f32 v[6:7], v[128:129], v[44:45], v[6:7] op_sel_hi:[1,0,1]
	v_pk_fma_f32 v[2:3], v[4:5], v[44:45], v[2:3] op_sel_hi:[1,0,1]
	v_pk_fma_f32 v[4:5], v[12:13], v[44:45], v[8:9] op_sel_hi:[1,0,1]
	v_pk_fma_f32 v[8:9], v[16:17], v[44:45], v[10:11] op_sel_hi:[1,0,1]
	v_mov_b32_e32 v50, v47
	s_waitcnt vmcnt(10)
	v_pk_fma_f32 v[6:7], v[188:189], v[64:65], v[6:7] op_sel_hi:[1,0,1]
	v_pk_fma_f32 v[2:3], v[190:191], v[64:65], v[2:3] op_sel_hi:[1,0,1]
	v_pk_fma_f32 v[4:5], v[192:193], v[64:65], v[4:5] op_sel_hi:[1,0,1]
	v_pk_fma_f32 v[8:9], v[194:195], v[64:65], v[8:9] op_sel_hi:[1,0,1]
	v_fmac_f32_e32 v124, v18, v64
	v_mov_b32_e32 v47, v52
	s_waitcnt vmcnt(9)
	v_pk_fma_f32 v[6:7], v[50:51], v[68:69], v[6:7] op_sel_hi:[1,0,1]
	v_pk_fma_f32 v[2:3], v[54:55], v[68:69], v[2:3] op_sel_hi:[1,0,1]
	v_pk_fma_f32 v[4:5], v[58:59], v[68:69], v[4:5] op_sel_hi:[1,0,1]
	v_pk_fma_f32 v[8:9], v[62:63], v[68:69], v[8:9] op_sel_hi:[1,0,1]
	v_fmac_f32_e32 v124, v19, v68
	s_waitcnt vmcnt(8)
	v_pk_fma_f32 v[6:7], v[46:47], v[72:73], v[6:7] op_sel_hi:[1,0,1]
	v_pk_fma_f32 v[2:3], v[70:71], v[72:73], v[2:3] op_sel_hi:[1,0,1]
	v_pk_fma_f32 v[4:5], v[66:67], v[72:73], v[4:5] op_sel_hi:[1,0,1]
	v_pk_fma_f32 v[8:9], v[74:75], v[72:73], v[8:9] op_sel_hi:[1,0,1]
	v_fmac_f32_e32 v124, v20, v72
	s_waitcnt vmcnt(7)
; DI void mod_phase(const Args& a, float* ldsf) {
;     ...
;             for (int u = 0; u < 16; ++u) {
; #pragma unroll
;                 for (int bb = 0; bb < 9; ++bb) acc[bb] = fmaf(ldsf[bb * 1024 + k0 + u], w[u], acc[bb]); } }
; #pragma unroll
;         for (int bb = 0; bb < 9; ++bb) red[(ks * 9 + bb) * 64 + cj] = acc[bb];
;         __syncthreads();
;         for (int i = tid; i < 9 * 64; i += NTHREADS) { const int bb = i >> 6, cj2 = i & 63; float s = 0.f;
; #pragma unroll
;             for (int k2 = 0; k2 < 8; ++k2) s += red[(k2 * 9 + bb) * 64 + cj2];
;             const int col2 = cgp * 64 + cj2; modv[(size_t)(l * 9 + bb) * 3072 + col2] = s + a.in[5][l * 3072 + col2]; }
	v_fmac_f32_e32 v124, v21, v76
	v_pk_fma_f32 v[6:7], v[196:197], v[76:77], v[6:7] op_sel_hi:[1,0,1]
	v_pk_fma_f32 v[2:3], v[198:199], v[76:77], v[2:3] op_sel_hi:[1,0,1]
	v_pk_fma_f32 v[4:5], v[200:201], v[76:77], v[4:5] op_sel_hi:[1,0,1]
	v_pk_fma_f32 v[8:9], v[202:203], v[76:77], v[8:9] op_sel_hi:[1,0,1]
	s_waitcnt vmcnt(6)
	v_pk_fma_f32 v[6:7], v[132:133], v[156:157], v[6:7] op_sel_hi:[1,0,1]
	v_pk_fma_f32 v[2:3], v[136:137], v[156:157], v[2:3] op_sel_hi:[1,0,1]
	v_pk_fma_f32 v[4:5], v[140:141], v[156:157], v[4:5] op_sel_hi:[1,0,1]
	v_pk_fma_f32 v[8:9], v[144:145], v[156:157], v[8:9] op_sel_hi:[1,0,1]
	v_fmac_f32_e32 v124, v38, v156
	s_waitcnt vmcnt(5)
	v_pk_fma_f32 v[6:7], v[114:115], v[104:105], v[6:7] op_sel_hi:[1,0,1]
	v_pk_fma_f32 v[2:3], v[134:135], v[104:105], v[2:3] op_sel_hi:[1,0,1]
	v_pk_fma_f32 v[4:5], v[138:139], v[104:105], v[4:5] op_sel_hi:[1,0,1]
	v_pk_fma_f32 v[8:9], v[142:143], v[104:105], v[8:9] op_sel_hi:[1,0,1]
	v_fmac_f32_e32 v124, v39, v104
	s_waitcnt vmcnt(4)
	v_pk_fma_f32 v[6:7], v[146:147], v[110:111], v[6:7] op_sel_hi:[1,0,1]
	v_pk_fma_f32 v[2:3], v[150:151], v[110:111], v[2:3] op_sel_hi:[1,0,1]
	v_pk_fma_f32 v[4:5], v[154:155], v[110:111], v[4:5] op_sel_hi:[1,0,1]
	v_pk_fma_f32 v[8:9], v[160:161], v[110:111], v[8:9] op_sel_hi:[1,0,1]
	v_fmac_f32_e32 v124, v40, v110
	s_waitcnt vmcnt(3)
	v_fmac_f32_e32 v124, v41, v166
	v_pk_fma_f32 v[6:7], v[116:117], v[166:167], v[6:7] op_sel_hi:[1,0,1]
	v_pk_fma_f32 v[2:3], v[148:149], v[166:167], v[2:3] op_sel_hi:[1,0,1]
	v_pk_fma_f32 v[4:5], v[152:153], v[166:167], v[4:5] op_sel_hi:[1,0,1]
	v_pk_fma_f32 v[8:9], v[158:159], v[166:167], v[8:9] op_sel_hi:[1,0,1]
	s_waitcnt lgkmcnt(0)
	v_mov_b32_e32 v52, v178
	s_waitcnt vmcnt(2)
	v_fmac_f32_e32 v124, v26, v170
	v_pk_fma_f32 v[6:7], v[162:163], v[170:171], v[6:7] op_sel_hi:[1,0,1]
	v_pk_fma_f32 v[2:3], v[164:165], v[170:171], v[2:3] op_sel_hi:[1,0,1]
	v_pk_fma_f32 v[4:5], v[168:169], v[170:171], v[4:5] op_sel_hi:[1,0,1]
	v_pk_fma_f32 v[8:9], v[176:177], v[170:171], v[8:9] op_sel_hi:[1,0,1]
	v_add_u32_e32 v123, 16, v123
	v_mov_b32_e32 v95, v101
	v_pk_mov_b32 v[100:101], v[178:179], v[100:101] op_sel:[1,0]
	s_waitcnt vmcnt(1)
	v_fmac_f32_e32 v124, v27, v172
	v_pk_fma_f32 v[6:7], v[48:49], v[172:173], v[6:7] op_sel_hi:[1,0,1]
	v_pk_fma_f32 v[2:3], v[52:53], v[172:173], v[2:3] op_sel_hi:[1,0,1]
	v_pk_fma_f32 v[4:5], v[56:57], v[172:173], v[4:5] op_sel_hi:[1,0,1]
	v_pk_fma_f32 v[8:9], v[60:61], v[172:173], v[8:9] op_sel_hi:[1,0,1]
	v_cmp_ge_i32_e64 s[6:7], v123, v69
	s_waitcnt vmcnt(0)
	v_fmac_f32_e32 v124, v28, v174
	v_pk_fma_f32 v[6:7], v[120:121], v[174:175], v[6:7] op_sel_hi:[1,0,1]
	v_pk_fma_f32 v[2:3], v[100:101], v[174:175], v[2:3] op_sel_hi:[1,0,1]
	v_pk_fma_f32 v[4:5], v[102:103], v[174:175], v[4:5] op_sel_hi:[1,0,1]
	v_pk_fma_f32 v[8:9], v[108:109], v[174:175], v[8:9] op_sel_hi:[1,0,1]
	v_add_u32_e32 v122, 64, v122
	s_or_b64 s[10:11], s[6:7], s[10:11]
	v_lshl_add_u64 v[84:85], v[84:85], 0, s[8:9]
	v_pk_fma_f32 v[86:87], v[118:119], v[112:113], v[6:7] op_sel_hi:[1,0,1]
	v_pk_fma_f32 v[88:89], v[94:95], v[112:113], v[2:3] op_sel_hi:[1,0,1]
	v_pk_fma_f32 v[90:91], v[96:97], v[112:113], v[4:5] op_sel_hi:[1,0,1]
	v_pk_fma_f32 v[92:93], v[98:99], v[112:113], v[8:9] op_sel_hi:[1,0,1]
	v_fmac_f32_e32 v124, v29, v112
	s_andn2_b64 exec, exec, s[10:11]
	s_cbranch_execnz .LBB0_21
	s_or_b64 exec, exec, s[10:11]
	ds_write2st64_b32 v113, v86, v87 offset0:144 offset1:145
	ds_write2st64_b32 v113, v88, v89 offset0:146 offset1:147
	ds_write2st64_b32 v113, v90, v91 offset0:148 offset1:149
	ds_write2st64_b32 v113, v92, v93 offset0:150 offset1:151
	ds_write_b32 v113, v124 offset:38912
	s_waitcnt lgkmcnt(0)
	s_barrier
	s_and_saveexec_b64 s[6:7], s[4:5]
	s_cbranch_execz .LBB0_19
	s_mul_i32 s10, s12, 0xc00
	v_add_u32_e32 v2, s10, v82
	v_readlane_b32 s10, v253, 7
	v_ashrrev_i32_e32 v3, 31, v2
	v_readlane_b32 s11, v253, 8
	s_mul_i32 s12, s12, 9
	v_lshl_add_u64 v[2:3], v[2:3], 2, s[82:83]
	v_lshl_add_u64 v[4:5], v[82:83], 2, s[10:11]
	s_mov_b64 s[10:11], 0
	v_mov_b32_e32 v6, v78

; DI unsigned cvt_pk_bf16(float lo, float hi) { unsigned r; asm volatile("v_cvt_pk_bf16_f32 %0, %1, %2" : "=v"(r) : "v"(lo), "v"(hi)); return r; }
; DI void convert_wt(const float* __restrict__ W, bf16_t* __restrict__ Wt, int K, int N, float* tl) {
;     ...
;     for (int tile = blockIdx.x; tile < ntiles; tile += gridDim.x) {
;         const int k0 = (tile / ntn) * 64, n0 = (tile % ntn) * 64, tj = tid & 63, ti = tid >> 6;
; #pragma unroll
;         for (int ii = 0; ii < 8; ++ii) { const int k = ti * 8 + ii; tl[k * 65 + tj] = W[(size_t)(k0 + k) * N + n0 + tj]; }
;         __syncthreads();
;         const int n = tid >> 3, ks = (tid & 7) * 8;
;         u32x4 w;
;         w[0] = cvt_pk_bf16(tl[(ks + 0) * 65 + n], tl[(ks + 1) * 65 + n]); w[1] = cvt_pk_bf16(tl[(ks + 2) * 65 + n], tl[(ks + 3) * 65 + n]);
;         w[2] = cvt_pk_bf16(tl[(ks + 4) * 65 + n], tl[(ks + 5) * 65 + n]); w[3] = cvt_pk_bf16(tl[(ks + 6) * 65 + n], tl[(ks + 7) * 65 + n]);
;         *(u32x4*)(Wt + (size_t)(n0 + n) * K + k0 + ks) = w;
;         __syncthreads();
;     }
.LBB0_42:
	s_mul_hi_i32 s4, s3, 0x66666667
	s_lshr_b32 s5, s4, 31
	s_ashr_i32 s4, s4, 4
	s_add_i32 s5, s4, s5
	s_lshl_b32 s4, s5, 6
	s_mulk_i32 s5, 0xf600
	s_add_i32 s6, s0, s5
	s_ashr_i32 s7, s6, 31
	v_add_u32_e32 v19, s4, v6
	v_add_u32_e32 v26, s4, v9
	v_add_u32_e32 v28, s4, v10
	v_add_u32_e32 v30, s4, v11
	v_lshl_add_u64 v[20:21], s[6:7], 2, v[4:5]
	v_add_u32_e32 v24, s4, v8
	v_add_u32_e32 v32, s4, v12
	v_add_u32_e32 v34, s4, v13
	v_add_u32_e32 v36, s4, v14
	v_mad_i64_i32 v[22:23], s[8:9], v19, s2, v[20:21]
	v_mad_i64_i32 v[26:27], s[8:9], v26, s2, v[20:21]
	v_mad_i64_i32 v[28:29], s[8:9], v28, s2, v[20:21]
	v_mad_i64_i32 v[30:31], s[8:9], v30, s2, v[20:21]
	v_mad_i64_i32 v[24:25], s[8:9], v24, s2, v[20:21]
	v_mad_i64_i32 v[32:33], s[8:9], v32, s2, v[20:21]
	v_mad_i64_i32 v[34:35], s[8:9], v34, s2, v[20:21]
	v_mad_i64_i32 v[20:21], s[8:9], v36, s2, v[20:21]
	global_load_dword v19, v[22:23], off nt
	s_nop 0
	global_load_dword v22, v[24:25], off nt
	global_load_dword v23, v[26:27], off nt
	s_nop 0
	global_load_dword v26, v[28:29], off nt
	global_load_dword v27, v[30:31], off nt
	s_nop 0
	global_load_dword v28, v[32:33], off nt
	global_load_dword v29, v[34:35], off nt
	global_load_dword v30, v[20:21], off nt
	v_add_u32_e32 v20, s6, v1
	v_ashrrev_i32_e32 v21, 31, v20
	v_lshlrev_b64 v[20:21], 11, v[20:21]
	s_ashr_i32 s5, s4, 31
	v_lshl_add_u64 v[20:21], s[28:29], 0, v[20:21]
	v_lshl_add_u64 v[24:25], s[4:5], 1, v[20:21]
	s_add_i32 s3, s3, s30
	s_add_i32 s0, s0, s1
	s_cmpk_lt_i32 s3, 0x280
	v_lshl_add_u64 v[24:25], v[24:25], 0, v[2:3]
	s_waitcnt vmcnt(6)
	ds_write2_b32 v15, v19, v22 offset1:65
	s_waitcnt vmcnt(4)
	ds_write2_b32 v15, v23, v26 offset0:130 offset1:195
	s_waitcnt vmcnt(2)
	ds_write2_b32 v17, v27, v28 offset0:4 offset1:69
	s_waitcnt vmcnt(1)
	ds_write_b32 v15, v29 offset:1560
	s_waitcnt vmcnt(0)
	ds_write_b32 v16, v30
	s_waitcnt lgkmcnt(0)
	s_barrier
	ds_read2_b32 v[20:21], v7 offset1:65
	s_waitcnt lgkmcnt(0)
	v_cvt_pk_bf16_f32 v20, v20, v21
	ds_read2_b32 v[22:23], v7 offset0:130 offset1:195
	s_waitcnt lgkmcnt(0)
	v_cvt_pk_bf16_f32 v21, v22, v23
	ds_read2_b32 v[22:23], v18 offset0:4 offset1:69
	s_waitcnt lgkmcnt(0)
	v_cvt_pk_bf16_f32 v22, v22, v23
	ds_read2_b32 v[26:27], v18 offset0:134 offset1:199
	s_waitcnt lgkmcnt(0)
	v_cvt_pk_bf16_f32 v23, v26, v27
	global_store_dwordx4 v[24:25], v[20:23], off
	s_barrier
	s_cbranch_scc1 .LBB0_42

; DI unsigned cvt_pk_bf16(float lo, float hi) { unsigned r; asm volatile("v_cvt_pk_bf16_f32 %0, %1, %2" : "=v"(r) : "v"(lo), "v"(hi)); return r; }
; DI void convert_wt(const float* __restrict__ W, bf16_t* __restrict__ Wt, int K, int N, float* tl) {
;     ...
;     for (int tile = blockIdx.x; tile < ntiles; tile += gridDim.x) {
;         const int k0 = (tile / ntn) * 64, n0 = (tile % ntn) * 64, tj = tid & 63, ti = tid >> 6;
; #pragma unroll
;         for (int ii = 0; ii < 8; ++ii) { const int k = ti * 8 + ii; tl[k * 65 + tj] = W[(size_t)(k0 + k) * N + n0 + tj]; }
;         __syncthreads();
;         const int n = tid >> 3, ks = (tid & 7) * 8;
;         u32x4 w;
;         w[0] = cvt_pk_bf16(tl[(ks + 0) * 65 + n], tl[(ks + 1) * 65 + n]); w[1] = cvt_pk_bf16(tl[(ks + 2) * 65 + n], tl[(ks + 3) * 65 + n]);
;         w[2] = cvt_pk_bf16(tl[(ks + 4) * 65 + n], tl[(ks + 5) * 65 + n]); w[3] = cvt_pk_bf16(tl[(ks + 6) * 65 + n], tl[(ks + 7) * 65 + n]);
;         *(u32x4*)(Wt + (size_t)(n0 + n) * K + k0 + ks) = w;
;         __syncthreads();
;     }
.LBB0_45:
	s_ashr_i32 s0, s6, 31
	s_lshr_b32 s0, s0, 28
	s_add_i32 s0, s6, s0
	s_ashr_i32 s1, s0, 4
	s_lshl_b32 s0, s1, 6
	s_lshl_b32 s1, s1, 10
	s_sub_i32 s4, s2, s1
	v_add_u32_e32 v20, s0, v6
	v_add_u32_e32 v22, s0, v8
	v_add_u32_e32 v26, s0, v10
	v_add_u32_e32 v28, s0, v11
	v_add_u32_e32 v30, s0, v12
	v_add_u32_e32 v24, s0, v9
	v_add_u32_e32 v32, s0, v13
	v_add_u32_e32 v34, s0, v14
	s_ashr_i32 s5, s4, 31
	v_ashrrev_i32_e32 v21, 31, v20
	v_ashrrev_i32_e32 v23, 31, v22
	v_ashrrev_i32_e32 v27, 31, v26
	v_ashrrev_i32_e32 v29, 31, v28
	v_ashrrev_i32_e32 v31, 31, v30
	v_ashrrev_i32_e32 v25, 31, v24
	v_ashrrev_i32_e32 v33, 31, v32
	v_ashrrev_i32_e32 v35, 31, v34
	v_lshl_add_u64 v[36:37], s[4:5], 2, v[4:5]
	v_lshlrev_b64 v[20:21], 12, v[20:21]
	v_lshlrev_b64 v[22:23], 12, v[22:23]
	v_lshlrev_b64 v[26:27], 12, v[26:27]
	v_lshlrev_b64 v[28:29], 12, v[28:29]
	v_lshlrev_b64 v[30:31], 12, v[30:31]
	v_lshlrev_b64 v[24:25], 12, v[24:25]
	v_lshlrev_b64 v[32:33], 12, v[32:33]
	v_lshlrev_b64 v[34:35], 12, v[34:35]
	v_lshl_add_u64 v[20:21], v[36:37], 0, v[20:21]
	v_lshl_add_u64 v[22:23], v[36:37], 0, v[22:23]
	v_lshl_add_u64 v[26:27], v[36:37], 0, v[26:27]
	v_lshl_add_u64 v[28:29], v[36:37], 0, v[28:29]
	v_lshl_add_u64 v[30:31], v[36:37], 0, v[30:31]
	v_lshl_add_u64 v[24:25], v[36:37], 0, v[24:25]
	v_lshl_add_u64 v[32:33], v[36:37], 0, v[32:33]
	v_lshl_add_u64 v[34:35], v[36:37], 0, v[34:35]
	global_load_dword v19, v[20:21], off nt
	s_nop 0
	global_load_dword v22, v[22:23], off nt
	s_nop 0
	global_load_dword v23, v[24:25], off nt
	s_nop 0
	global_load_dword v26, v[26:27], off nt
	s_nop 0
	global_load_dword v27, v[28:29], off nt
	s_nop 0
	global_load_dword v28, v[30:31], off nt
	global_load_dword v29, v[32:33], off nt
	s_nop 0
	global_load_dword v30, v[34:35], off nt
	v_add_u32_e32 v20, s4, v1
	v_ashrrev_i32_e32 v21, 31, v20
	v_lshlrev_b64 v[20:21], 11, v[20:21]
	s_ashr_i32 s1, s0, 31
	v_lshl_add_u64 v[20:21], s[54:55], 0, v[20:21]
	v_lshl_add_u64 v[24:25], s[0:1], 1, v[20:21]
	s_add_i32 s6, s6, s30
	s_add_i32 s2, s2, s3
	s_cmpk_lt_i32 s6, 0x100
	v_lshl_add_u64 v[24:25], v[24:25], 0, v[2:3]
	s_waitcnt vmcnt(6)
	ds_write2_b32 v15, v19, v22 offset1:65
	s_waitcnt vmcnt(4)
	ds_write2_b32 v15, v23, v26 offset0:130 offset1:195
	s_waitcnt vmcnt(2)
	ds_write2_b32 v17, v27, v28 offset0:4 offset1:69
	s_waitcnt vmcnt(1)
	ds_write_b32 v15, v29 offset:1560
	s_waitcnt vmcnt(0)
	ds_write_b32 v16, v30
	s_waitcnt lgkmcnt(0)
	s_barrier
	ds_read2_b32 v[20:21], v7 offset1:65
	s_waitcnt lgkmcnt(0)
	v_cvt_pk_bf16_f32 v20, v20, v21
	ds_read2_b32 v[22:23], v7 offset0:130 offset1:195
	s_waitcnt lgkmcnt(0)
	v_cvt_pk_bf16_f32 v21, v22, v23
	ds_read2_b32 v[22:23], v18 offset0:4 offset1:69
	s_waitcnt lgkmcnt(0)
	v_cvt_pk_bf16_f32 v22, v22, v23
	ds_read2_b32 v[26:27], v18 offset0:134 offset1:199
	s_waitcnt lgkmcnt(0)
	v_cvt_pk_bf16_f32 v23, v26, v27
	global_store_dwordx4 v[24:25], v[20:23], off
	s_barrier
	s_cbranch_scc1 .LBB0_45

; DI void store8(bf16_t* p, f32x4 a, f32x4 b) { u32x4 w = {cvt_pk_bf16(a[0], a[1]), cvt_pk_bf16(a[2], a[3]), cvt_pk_bf16(b[0], b[1]), cvt_pk_bf16(b[2], b[3])}; *(u32x4*)p = w; }
; DI void modulate_phase(const Args& a) {
;     ...
;     for (size_t i = gt; i < (size_t)TT * 128; i += gs) {
;         const int row = (int)(i >> 7), c8 = (int)(i & 127) * 8;
;         const float* xr = row < TL ? a.in[0] + (size_t)row * 1024 : a.in[2] + (size_t)(row - TL) * 1024;
;         const int bb = row < TL ? (row >> 12) : 8;
;         const float* mv = modv + (size_t)bb * 3072;
;         const f32x4 x0 = *(const f32x4*)(xr + c8), x1 = *(const f32x4*)(xr + c8 + 4);
;         const f32x4 sh0 = *(const f32x4*)(mv + c8), sh1 = *(const f32x4*)(mv + c8 + 4), sc0 = *(const f32x4*)(mv + 1024 + c8), sc1 = *(const f32x4*)(mv + 1024 + c8 + 4);
;         store8(h + (size_t)row * 1024 + c8, x0 * (sc0 + 1.f) + sh0, x1 * (sc1 + 1.f) + sh1);
;     }
.LBB0_112:
	s_or_b64 exec, exec, s[20:21]
	v_cmp_gt_u64_e32 vcc, s[14:15], v[0:1]
	v_and_b32_e32 v13, 0x3f8, v2
	v_lshlrev_b64 v[8:9], 11, v[8:9]
	v_cndmask_b32_e32 v6, v12, v0, vcc
	v_lshrrev_b32_e32 v6, 19, v6
	v_mad_u64_u32 v[14:15], s[20:21], v6, s2, v[4:5]
	v_lshlrev_b32_e32 v6, 2, v13
	v_lshl_add_u64 v[34:35], v[14:15], 0, v[6:7]
	v_add_co_u32_e32 v14, vcc, s3, v34
	v_lshl_add_u64 v[18:19], v[34:35], 0, s[16:17]
	s_nop 0
	v_addc_co_u32_e32 v15, vcc, 0, v35, vcc
	global_load_dwordx4 v[14:17], v[14:15], off
	v_lshl_add_u64 v[10:11], v[10:11], 0, v[6:7]
	global_load_dwordx4 v[18:21], v[18:19], off offset:16
	s_nop 0
	global_load_dwordx4 v[22:25], v[34:35], off
	global_load_dwordx4 v[26:29], v[10:11], off nt
	global_load_dwordx4 v[30:33], v[10:11], off offset:16 nt
	s_nop 0
	global_load_dwordx4 v[34:37], v[34:35], off offset:16
	v_lshl_add_u64 v[0:1], v[0:1], 0, s[4:5]
	v_lshl_add_u64 v[8:9], s[90:91], 0, v[8:9]
	v_lshlrev_b32_e32 v6, 1, v13
	v_cmp_lt_u64_e32 vcc, s[18:19], v[0:1]
	v_lshl_add_u64 v[38:39], v[8:9], 0, v[6:7]
	s_or_b64 s[8:9], vcc, s[8:9]
	v_lshl_add_u64 v[2:3], v[2:3], 0, s[6:7]
	s_waitcnt vmcnt(5)
	v_pk_add_f32 v[8:9], v[16:17], 1.0 op_sel_hi:[1,0]
	v_pk_add_f32 v[10:11], v[14:15], 1.0 op_sel_hi:[1,0]
	s_waitcnt vmcnt(4)
	v_pk_add_f32 v[16:17], v[18:19], 1.0 op_sel_hi:[1,0]
	v_pk_add_f32 v[14:15], v[20:21], 1.0 op_sel_hi:[1,0]
	s_waitcnt vmcnt(2)
	v_pk_fma_f32 v[18:19], v[28:29], v[8:9], v[24:25]
	v_pk_fma_f32 v[8:9], v[26:27], v[10:11], v[22:23]
	s_waitcnt vmcnt(0)
	v_pk_fma_f32 v[10:11], v[30:31], v[16:17], v[34:35]
	v_pk_fma_f32 v[14:15], v[32:33], v[14:15], v[36:37]
	v_cvt_pk_bf16_f32 v8, v8, v9
	v_cvt_pk_bf16_f32 v9, v18, v19
	v_cvt_pk_bf16_f32 v10, v10, v11
	s_nop 0
	v_cvt_pk_bf16_f32 v11, v14, v15
	global_store_dwordx4 v[38:39], v[8:11], off
	s_andn2_b64 exec, exec, s[8:9]
	s_cbranch_execz .LBB0_117

; DI float bflo(unsigned w) { return __uint_as_float(w << 16); }
; DI float bfhi(unsigned w) { return __uint_as_float(w & 0xffff0000u); }
; template <int NR>
; DI void ln_rows(const Args& a, int l, int row0, int lane, const f32x4 (&lgv)[4], const f32x4 (&lbv)[4], const f32x4 (&gate)[4], const f32x4 (&sh)[4], const f32x4 (&sc1)[4]) {
;     ...
;     for (int k = 0; k < NR; ++k) { const int row = row0 + k; s[k] = 0.f;
;         const float* xr = row < TL ? xlat + (size_t)row * 1024 : xctx + (size_t)(row - TL) * 1024;
; #pragma unroll
;         for (int i = 0; i < 4; ++i) { const int col = 4 * lane + 256 * i;
;             const f32x4 xv = *(const f32x4*)(xr + col); const u32x2 yw = *(const u32x2*)(y + (size_t)row * 1024 + col);
;             f32x4 yv; yv[0] = bflo(yw[0]); yv[1] = bfhi(yw[0]); yv[2] = bflo(yw[1]); yv[3] = bfhi(yw[1]);
;             v[k][i] = xv * ALPHA + gate[i] * yv; s[k] += v[k][i][0] + v[k][i][1] + v[k][i][2] + v[k][i][3]; } }
.LBB0_975:
	global_load_dwordx2 v[138:139], v[124:125], off nt
	global_load_dwordx2 v[140:141], v[124:125], off offset:512 nt
	global_load_dwordx2 v[142:143], v[124:125], off offset:1024 nt
	global_load_dwordx2 v[144:145], v[124:125], off offset:1536 nt
	global_load_dwordx4 v[76:79], v[126:127], off offset:-2048 nt
	global_load_dwordx4 v[72:75], v[126:127], off offset:-1024 nt
	global_load_dwordx4 v[68:71], v[126:127], off nt
	global_load_dwordx4 v[64:67], v[126:127], off offset:1024 nt
	v_add_u32_e32 v81, s69, v94
	v_add_u32_e32 v80, 4, v81
	v_add_u32_e32 v103, 3, v81
	v_add_u32_e32 v82, 5, v81
	v_ashrrev_i32_e32 v81, 31, v80
	v_lshlrev_b64 v[136:137], 11, v[80:81]
	v_lshl_add_u64 v[150:151], v[90:91], 0, v[136:137]
	global_load_dwordx2 v[152:153], v[150:151], off nt
	v_lshlrev_b64 v[134:135], 12, v[80:81]
	v_lshl_add_u64 v[80:81], v[86:87], 0, v[134:135]
	global_load_dwordx4 v[146:149], v[80:81], off nt
	v_ashrrev_i32_e32 v83, 31, v82
	v_lshlrev_b64 v[132:133], 12, v[82:83]
	v_lshlrev_b64 v[130:131], 11, v[82:83]
	global_load_dwordx2 v[188:189], v[150:151], off offset:512 nt
	global_load_dwordx4 v[156:159], v[80:81], off offset:1024 nt
	global_load_dwordx4 v[170:173], v[80:81], off offset:2048 nt
	s_nop 0
	global_load_dwordx4 v[80:83], v[80:81], off offset:3072 nt
	s_nop 0
	global_load_dwordx2 v[190:191], v[150:151], off offset:1024 nt
	global_load_dwordx2 v[192:193], v[150:151], off offset:1536 nt
	s_movk_i32 s0, 0x7ffe
	v_mov_b32_e32 v89, s21
	v_mov_b32_e32 v95, s20
	v_lshl_add_u64 v[154:155], s[18:19], 0, v[132:133]
	v_cmp_gt_i32_e64 s[6:7], s0, v103
	v_lshl_add_u64 v[160:161], v[90:91], 0, v[130:131]
	global_load_dwordx2 v[194:195], v[160:161], off nt
	global_load_dwordx2 v[196:197], v[160:161], off offset:512 nt
	v_cndmask_b32_e64 v151, v89, v155, s[6:7]
	v_cndmask_b32_e64 v150, v95, v154, s[6:7]
	v_lshl_add_u64 v[198:199], v[150:151], 0, v[180:181]
	global_load_dwordx4 v[184:187], v[198:199], off nt
	s_mov_b64 s[8:9], -1
	s_waitcnt vmcnt(18)
	v_lshlrev_b32_e32 v150, 16, v138
	v_and_b32_e32 v151, 0xffff0000, v138
	s_waitcnt vmcnt(17)
	v_lshlrev_b32_e32 v154, 16, v140
	v_and_b32_e32 v155, 0xffff0000, v140
	v_lshlrev_b32_e32 v138, 16, v139
	v_and_b32_e32 v139, 0xffff0000, v139
	v_lshlrev_b32_e32 v140, 16, v141
	v_and_b32_e32 v141, 0xffff0000, v141
	s_waitcnt vmcnt(16)
	v_lshlrev_b32_e32 v162, 16, v142
	v_and_b32_e32 v163, 0xffff0000, v142
	s_waitcnt vmcnt(15)
	v_lshlrev_b32_e32 v164, 16, v144
	v_and_b32_e32 v165, 0xffff0000, v144
	v_lshlrev_b32_e32 v144, 16, v145
	v_and_b32_e32 v145, 0xffff0000, v145
	v_pk_mul_f32 v[150:151], v[60:61], v[150:151]
	v_pk_mul_f32 v[154:155], v[56:57], v[154:155]
	v_pk_mul_f32 v[138:139], v[62:63], v[138:139]
	v_pk_mul_f32 v[140:141], v[58:59], v[140:141]
	v_pk_mul_f32 v[162:163], v[52:53], v[162:163]
	v_pk_mul_f32 v[200:201], v[48:49], v[164:165]
	v_pk_mul_f32 v[144:145], v[50:51], v[144:145]
	s_waitcnt vmcnt(14)
	v_pk_fma_f32 v[178:179], v[76:77], s[44:45], v[150:151] op_sel_hi:[1,0,1]
	s_waitcnt vmcnt(13)
	v_pk_fma_f32 v[174:175], v[72:73], s[44:45], v[154:155] op_sel_hi:[1,0,1]
	v_lshlrev_b32_e32 v142, 16, v143
	v_and_b32_e32 v143, 0xffff0000, v143
	v_pk_fma_f32 v[176:177], v[78:79], s[44:45], v[138:139] op_sel_hi:[1,0,1]
	v_pk_fma_f32 v[168:169], v[74:75], s[44:45], v[140:141] op_sel_hi:[1,0,1]
	s_waitcnt vmcnt(12)
	v_pk_fma_f32 v[166:167], v[68:69], s[44:45], v[162:163] op_sel_hi:[1,0,1]
	s_waitcnt vmcnt(11)
	v_pk_fma_f32 v[154:155], v[66:67], s[44:45], v[144:145] op_sel_hi:[1,0,1]
	v_pk_fma_f32 v[162:163], v[64:65], s[44:45], v[200:201] op_sel_hi:[1,0,1]
	v_mov_b32_e32 v64, v178
	v_mov_b32_e32 v65, v174
	v_mov_b32_e32 v66, v179
	v_mov_b32_e32 v67, v175
	v_pk_mul_f32 v[142:143], v[54:55], v[142:143]
	v_mov_b32_e32 v68, v176
	v_mov_b32_e32 v69, v168
	v_pk_add_f32 v[64:65], v[64:65], v[66:67]
	v_pk_fma_f32 v[164:165], v[70:71], s[44:45], v[142:143] op_sel_hi:[1,0,1]
	v_mov_b32_e32 v70, v177
	v_mov_b32_e32 v71, v169
	v_pk_add_f32 v[64:65], v[68:69], v[64:65]
	v_mov_b32_e32 v72, v166
	v_pk_add_f32 v[64:65], v[70:71], v[64:65]
	v_mov_b32_e32 v73, v162
	v_mov_b32_e32 v74, v167
	v_mov_b32_e32 v75, v163
	v_add_f32_e32 v64, 0, v64
	v_pk_add_f32 v[66:67], v[72:73], v[74:75]
	v_add_f32_e32 v72, v64, v65
	v_mov_b32_e32 v64, v164
	v_mov_b32_e32 v65, v154
	v_pk_add_f32 v[68:69], v[64:65], v[66:67]
	v_mov_b32_e32 v70, v165
	v_mov_b32_e32 v71, v155
	global_load_dwordx4 v[64:67], v[198:199], off offset:1024 nt
	v_pk_add_f32 v[68:69], v[70:71], v[68:69]
	s_waitcnt vmcnt(11)
	v_lshlrev_b32_e32 v70, 16, v153
	v_add_f32_e32 v68, v72, v68
	v_add_f32_e32 v89, v68, v69
	v_lshlrev_b32_e32 v68, 16, v152
	v_and_b32_e32 v69, 0xffff0000, v152
	v_and_b32_e32 v71, 0xffff0000, v153
	v_pk_mul_f32 v[68:69], v[60:61], v[68:69]
	v_pk_mul_f32 v[70:71], v[62:63], v[70:71]
	s_waitcnt vmcnt(10)
	v_pk_fma_f32 v[152:153], v[146:147], s[44:45], v[68:69] op_sel_hi:[1,0,1]
	v_pk_fma_f32 v[150:151], v[148:149], s[44:45], v[70:71] op_sel_hi:[1,0,1]
	s_waitcnt vmcnt(9)
	v_lshlrev_b32_e32 v68, 16, v188
	v_and_b32_e32 v69, 0xffff0000, v188
	v_lshlrev_b32_e32 v70, 16, v189
	global_load_dwordx2 v[74:75], v[160:161], off offset:1024 nt
	global_load_dwordx2 v[76:77], v[160:161], off offset:1536 nt
	v_and_b32_e32 v71, 0xffff0000, v189
	v_pk_mul_f32 v[68:69], v[56:57], v[68:69]
	v_pk_mul_f32 v[70:71], v[58:59], v[70:71]
	s_waitcnt vmcnt(10)
	v_pk_fma_f32 v[156:157], v[156:157], s[44:45], v[68:69] op_sel_hi:[1,0,1]
	v_pk_fma_f32 v[140:141], v[158:159], s[44:45], v[70:71] op_sel_hi:[1,0,1]
	global_load_dwordx4 v[68:71], v[198:199], off offset:2048 nt
	global_load_dwordx4 v[158:161], v[198:199], off offset:3072 nt
	v_mov_b32_e32 v72, v152
	v_mov_b32_e32 v73, v156
	v_mov_b32_e32 v78, v153
	v_mov_b32_e32 v79, v157
	v_pk_add_f32 v[72:73], v[72:73], v[78:79]
	v_mov_b32_e32 v78, v150
	v_mov_b32_e32 v79, v140
	v_pk_add_f32 v[72:73], v[78:79], v[72:73]
	v_mov_b32_e32 v78, v151
	v_mov_b32_e32 v79, v141
	v_pk_add_f32 v[72:73], v[78:79], v[72:73]
	s_waitcnt vmcnt(9)
; DI float bflo(unsigned w) { return __uint_as_float(w << 16); }
; DI float bfhi(unsigned w) { return __uint_as_float(w & 0xffff0000u); }
; template <int NR>
; DI void ln_rows(const Args& a, int l, int row0, int lane, const f32x4 (&lgv)[4], const f32x4 (&lbv)[4], const f32x4 (&gate)[4], const f32x4 (&sh)[4], const f32x4 (&sc1)[4]) {
;     ...
;         for (int i = 0; i < 4; ++i) { const int col = 4 * lane + 256 * i;
;             const f32x4 xv = *(const f32x4*)(xr + col); const u32x2 yw = *(const u32x2*)(y + (size_t)row * 1024 + col);
;             f32x4 yv; yv[0] = bflo(yw[0]); yv[1] = bfhi(yw[0]); yv[2] = bflo(yw[1]); yv[3] = bfhi(yw[1]);
;             v[k][i] = xv * ALPHA + gate[i] * yv; s[k] += v[k][i][0] + v[k][i][1] + v[k][i][2] + v[k][i][3]; } }
;     float mean[NR], rstd[NR];
; #pragma unroll
;     for (int k = 0; k < NR; ++k) mean[k] = wave_sum(s[k]) * (1.f / 1024.f);
	v_lshlrev_b32_e32 v78, 16, v191
	v_add_f32_e32 v72, 0, v72
	v_add_f32_e32 v95, v72, v73
	v_lshlrev_b32_e32 v72, 16, v190
	v_and_b32_e32 v73, 0xffff0000, v190
	v_and_b32_e32 v79, 0xffff0000, v191
	v_pk_mul_f32 v[72:73], v[52:53], v[72:73]
	v_pk_mul_f32 v[78:79], v[54:55], v[78:79]
	v_pk_fma_f32 v[148:149], v[170:171], s[44:45], v[72:73] op_sel_hi:[1,0,1]
	s_waitcnt vmcnt(8)
	v_lshlrev_b32_e32 v72, 16, v192
	v_and_b32_e32 v73, 0xffff0000, v192
	v_pk_fma_f32 v[146:147], v[172:173], s[44:45], v[78:79] op_sel_hi:[1,0,1]
	v_lshlrev_b32_e32 v78, 16, v193
	v_and_b32_e32 v79, 0xffff0000, v193
	v_pk_mul_f32 v[72:73], v[48:49], v[72:73]
	v_pk_mul_f32 v[78:79], v[50:51], v[78:79]
	v_pk_fma_f32 v[142:143], v[80:81], s[44:45], v[72:73] op_sel_hi:[1,0,1]
	v_pk_fma_f32 v[138:139], v[82:83], s[44:45], v[78:79] op_sel_hi:[1,0,1]
	v_mov_b32_e32 v72, v148
	v_mov_b32_e32 v73, v142
	v_mov_b32_e32 v78, v149
	v_mov_b32_e32 v79, v143
	v_pk_add_f32 v[72:73], v[72:73], v[78:79]
	v_mov_b32_e32 v78, v146
	v_mov_b32_e32 v79, v138
	v_pk_add_f32 v[72:73], v[78:79], v[72:73]
	v_mov_b32_e32 v78, v147
	v_mov_b32_e32 v79, v139
	v_pk_add_f32 v[72:73], v[78:79], v[72:73]
	s_waitcnt vmcnt(7)
	v_lshlrev_b32_e32 v78, 16, v195
	v_add_f32_e32 v72, v95, v72
	v_add_f32_e32 v95, v72, v73
	v_lshlrev_b32_e32 v72, 16, v194
	v_and_b32_e32 v73, 0xffff0000, v194
	v_and_b32_e32 v79, 0xffff0000, v195
	v_pk_mul_f32 v[72:73], v[60:61], v[72:73]
	v_pk_mul_f32 v[78:79], v[62:63], v[78:79]
	s_waitcnt vmcnt(5)
	v_pk_fma_f32 v[82:83], v[184:185], s[44:45], v[72:73] op_sel_hi:[1,0,1]
	v_lshlrev_b32_e32 v72, 16, v196
	v_and_b32_e32 v73, 0xffff0000, v196
	v_pk_fma_f32 v[80:81], v[186:187], s[44:45], v[78:79] op_sel_hi:[1,0,1]
	v_lshlrev_b32_e32 v78, 16, v197
	v_and_b32_e32 v79, 0xffff0000, v197
	v_pk_mul_f32 v[144:145], v[56:57], v[72:73]
	v_pk_mul_f32 v[72:73], v[58:59], v[78:79]
	s_waitcnt vmcnt(4)
	v_pk_fma_f32 v[78:79], v[64:65], s[44:45], v[144:145] op_sel_hi:[1,0,1]
	v_pk_fma_f32 v[72:73], v[66:67], s[44:45], v[72:73] op_sel_hi:[1,0,1]
	v_mov_b32_e32 v64, v82
	v_mov_b32_e32 v65, v78
	v_mov_b32_e32 v66, v83
	v_mov_b32_e32 v67, v79
	v_pk_add_f32 v[64:65], v[64:65], v[66:67]
	v_mov_b32_e32 v66, v80
	v_mov_b32_e32 v67, v72
	v_pk_add_f32 v[64:65], v[66:67], v[64:65]
	v_mov_b32_e32 v66, v81
	v_mov_b32_e32 v67, v73
	v_pk_add_f32 v[64:65], v[66:67], v[64:65]
	s_waitcnt vmcnt(3)
	v_lshlrev_b32_e32 v66, 16, v75
	v_and_b32_e32 v67, 0xffff0000, v75
	v_add_f32_e32 v64, 0, v64
	v_pk_mul_f32 v[66:67], v[54:55], v[66:67]
	v_add_f32_e32 v103, v64, v65
	v_lshlrev_b32_e32 v64, 16, v74
	v_and_b32_e32 v65, 0xffff0000, v74
	s_waitcnt vmcnt(1)
	v_pk_fma_f32 v[70:71], v[70:71], s[44:45], v[66:67] op_sel_hi:[1,0,1]
	v_lshlrev_b32_e32 v66, 16, v77
	v_and_b32_e32 v67, 0xffff0000, v77
	v_pk_mul_f32 v[64:65], v[52:53], v[64:65]
	v_pk_mul_f32 v[66:67], v[50:51], v[66:67]
	v_pk_fma_f32 v[74:75], v[68:69], s[44:45], v[64:65] op_sel_hi:[1,0,1]
	s_waitcnt vmcnt(0)
	v_pk_fma_f32 v[68:69], v[160:161], s[44:45], v[66:67] op_sel_hi:[1,0,1]
	v_mov_b32_e32 v67, v89
	v_mov_b32_e32 v212, v89
	s_mov_b32 s100, 0
	s_mov_b32 s101, -1
	v_permlane32_swap_b32_e32 v67, v212
	v_cndmask_b32_e64 v67, v212, v67, s[100:101]
	v_lshlrev_b32_e32 v64, 16, v76
	v_and_b32_e32 v65, 0xffff0000, v76
	v_pk_mul_f32 v[64:65], v[48:49], v[64:65]
	v_mov_b32_e32 v66, v75
	s_waitcnt lgkmcnt(0)
	v_add_f32_e32 v89, v89, v67
	v_mov_b32_e32 v105, v89
	v_mov_b32_e32 v212, v89
	s_mov_b32 s100, 0xffff0000
	s_mov_b32 s101, 0xffff0000
	v_permlane16_swap_b32_e32 v105, v212
	v_cndmask_b32_e64 v105, v212, v105, s[100:101]
	v_pk_fma_f32 v[76:77], v[158:159], s[44:45], v[64:65] op_sel_hi:[1,0,1]
	v_mov_b32_e32 v64, v74
	v_mov_b32_e32 v65, v76
	v_mov_b32_e32 v67, v77
	s_waitcnt lgkmcnt(0)
	v_add_f32_e32 v89, v89, v105
	s_nop 1
	v_mov_b32_dpp v105, v89 row_ror:8 row_mask:0xf bank_mask:0xf
	v_pk_add_f32 v[64:65], v[64:65], v[66:67]
	v_mov_b32_e32 v66, v70
	v_mov_b32_e32 v67, v68
	v_pk_add_f32 v[64:65], v[66:67], v[64:65]
	v_mov_b32_e32 v66, v71
	v_mov_b32_e32 v67, v69
	v_pk_add_f32 v[64:65], v[66:67], v[64:65]
	s_waitcnt lgkmcnt(0)
	v_add_f32_e32 v66, v89, v105
	s_nop 1
	v_mov_b32_dpp v67, v66 row_ror:4 row_mask:0xf bank_mask:0xf
	v_add_f32_e32 v64, v103, v64
	v_add_f32_e32 v64, v64, v65
	v_mov_b32_e32 v65, v64
	v_mov_b32_e32 v212, v64
	s_mov_b32 s100, 0
	s_mov_b32 s101, -1
	v_permlane32_swap_b32_e32 v65, v212
	v_cndmask_b32_e64 v65, v212, v65, s[100:101]
	v_mov_b32_e32 v89, v95
	v_mov_b32_e32 v212, v95
	s_mov_b32 s100, 0
	s_mov_b32 s101, -1
	v_permlane32_swap_b32_e32 v89, v212
	v_cndmask_b32_e64 v89, v212, v89, s[100:101]
	s_waitcnt lgkmcnt(2)
	v_add_f32_e32 v66, v66, v67
	s_nop 1
	v_mov_b32_dpp v67, v66 quad_perm:[2,3,0,1] row_mask:0xf bank_mask:0xf
	s_waitcnt lgkmcnt(2)
	v_add_f32_e32 v64, v64, v65
	v_mov_b32_e32 v65, v64
	v_mov_b32_e32 v212, v64
	s_mov_b32 s100, 0xffff0000
	s_mov_b32 s101, 0xffff0000
	v_permlane16_swap_b32_e32 v65, v212
	v_cndmask_b32_e64 v65, v212, v65, s[100:101]
	s_waitcnt lgkmcnt(2)
	v_add_f32_e32 v89, v95, v89
	s_waitcnt lgkmcnt(1)
	v_add_f32_e32 v66, v66, v67
	s_nop 1
	v_mov_b32_dpp v67, v66 quad_perm:[1,0,3,2] row_mask:0xf bank_mask:0xf
	v_mov_b32_e32 v95, v89
	v_mov_b32_e32 v212, v89
	s_mov_b32 s100, 0xffff0000
	s_mov_b32 s101, 0xffff0000
	v_permlane16_swap_b32_e32 v95, v212
	v_cndmask_b32_e64 v95, v212, v95, s[100:101]
	s_waitcnt lgkmcnt(2)
	v_add_f32_e32 v64, v64, v65
	s_nop 1
	v_mov_b32_dpp v65, v64 row_ror:8 row_mask:0xf bank_mask:0xf
	s_waitcnt lgkmcnt(2)
	v_add_f32_e32 v103, v66, v67
	s_waitcnt lgkmcnt(1)
; template <int NR>
; DI void ln_rows(const Args& a, int l, int row0, int lane, const f32x4 (&lgv)[4], const f32x4 (&lbv)[4], const f32x4 (&gate)[4], const f32x4 (&sh)[4], const f32x4 (&sc1)[4]) {
;     ...
;     for (int k = 0; k < NR; ++k) mean[k] = wave_sum(s[k]) * (1.f / 1024.f);
; #pragma unroll
;     for (int k = 0; k < NR; ++k) { float q = 0.f;
; #pragma unroll
;         for (int i = 0; i < 4; ++i) { v[k][i] = v[k][i] - mean[k]; q += v[k][i][0] * v[k][i][0] + v[k][i][1] * v[k][i][1] + v[k][i][2] * v[k][i][2] + v[k][i][3] * v[k][i][3]; }
;         rstd[k] = rsqrtf(wave_sum(q) * (1.f / 1024.f) + 1e-5f); }
	v_add_f32_e32 v89, v89, v95
	v_fmamk_f32 v179, v103, 0xba800000, v179
	v_fmamk_f32 v175, v103, 0xba800000, v175
	s_nop 1
	v_mov_b32_dpp v95, v89 row_ror:8 row_mask:0xf bank_mask:0xf
	v_fmac_f32_e32 v178, 0xba800000, v103
	v_fmac_f32_e32 v174, 0xba800000, v103
	v_mov_b32_e32 v66, v179
	v_mov_b32_e32 v67, v175
	s_waitcnt lgkmcnt(1)
	v_add_f32_e32 v105, v64, v65
	v_fmac_f32_e32 v176, 0xba800000, v103
	v_fmac_f32_e32 v168, 0xba800000, v103
	v_mov_b32_e32 v64, v178
	v_mov_b32_e32 v65, v174
	v_pk_mul_f32 v[66:67], v[66:67], v[66:67]
	v_fmamk_f32 v195, v103, 0xba800000, v167
	v_pk_fma_f32 v[64:65], v[64:65], v[64:65], v[66:67]
	v_mov_b32_e32 v66, v176
	v_mov_b32_e32 v67, v168
	v_fmac_f32_e32 v166, 0xba800000, v103
	v_fmamk_f32 v194, v103, 0xba800000, v163
	v_fmamk_f32 v177, v103, 0xba800000, v177
	v_pk_fma_f32 v[64:65], v[66:67], v[66:67], v[64:65]
	v_fmac_f32_e32 v164, 0xba800000, v103
	v_fmac_f32_e32 v162, 0xba800000, v103
	v_mov_b32_e32 v163, v166
	v_pk_mul_f32 v[66:67], v[194:195], v[194:195]
	v_fmamk_f32 v193, v103, 0xba800000, v169
	v_mov_b32_e32 v192, v177
	v_fmamk_f32 v188, v103, 0xba800000, v155
	v_fmac_f32_e32 v154, 0xba800000, v103
	v_pk_fma_f32 v[66:67], v[162:163], v[162:163], v[66:67]
	v_mov_b32_e32 v155, v164
	s_waitcnt lgkmcnt(0)
	v_add_f32_e32 v89, v89, v95
	v_pk_fma_f32 v[64:65], v[192:193], v[192:193], v[64:65]
	v_fmamk_f32 v189, v103, 0xba800000, v165
	v_pk_fma_f32 v[66:67], v[154:155], v[154:155], v[66:67]
	s_nop 1
	v_mov_b32_dpp v95, v89 row_ror:4 row_mask:0xf bank_mask:0xf
	s_nop 1
	v_mov_b32_dpp v107, v105 row_ror:4 row_mask:0xf bank_mask:0xf
	v_pk_fma_f32 v[66:67], v[188:189], v[188:189], v[66:67]
	v_add_f32_e32 v64, v64, v65
	v_add_f32_e32 v64, v67, v64
	v_add_f32_e32 v64, v66, v64
	v_mov_b32_e32 v65, v64
	v_mov_b32_e32 v212, v64
	s_mov_b32 s100, 0
	s_mov_b32 s101, -1
	v_permlane32_swap_b32_e32 v65, v212
	v_cndmask_b32_e64 v65, v212, v65, s[100:101]
	s_waitcnt lgkmcnt(2)
	v_add_f32_e32 v66, v89, v95
	s_waitcnt lgkmcnt(1)
	v_add_f32_e32 v89, v105, v107
	s_nop 1
	v_mov_b32_dpp v95, v89 quad_perm:[2,3,0,1] row_mask:0xf bank_mask:0xf
	s_nop 1
	v_mov_b32_dpp v67, v66 quad_perm:[2,3,0,1] row_mask:0xf bank_mask:0xf
	s_waitcnt lgkmcnt(2)
	v_add_f32_e32 v64, v64, v65
	v_mov_b32_e32 v65, v64
	v_mov_b32_e32 v212, v64
	s_mov_b32 s100, 0xffff0000
	s_mov_b32 s101, 0xffff0000
	v_permlane16_swap_b32_e32 v65, v212
	v_cndmask_b32_e64 v65, v212, v65, s[100:101]
	s_waitcnt lgkmcnt(2)
	v_add_f32_e32 v89, v89, v95
	s_waitcnt lgkmcnt(1)
	v_add_f32_e32 v66, v66, v67
	s_nop 1
	v_mov_b32_dpp v95, v89 quad_perm:[1,0,3,2] row_mask:0xf bank_mask:0xf
	s_nop 1
	v_mov_b32_dpp v67, v66 quad_perm:[1,0,3,2] row_mask:0xf bank_mask:0xf
	s_waitcnt lgkmcnt(2)
	v_add_f32_e32 v64, v64, v65
	s_nop 1
	v_mov_b32_dpp v65, v64 row_ror:8 row_mask:0xf bank_mask:0xf
	s_waitcnt lgkmcnt(2)
	v_add_f32_e32 v89, v89, v95
	s_waitcnt lgkmcnt(1)
	v_add_f32_e32 v66, v66, v67
	v_fmamk_f32 v172, v89, 0xba800000, v83
	v_fmamk_f32 v173, v89, 0xba800000, v79
	v_fmac_f32_e32 v78, 0xba800000, v89
	v_fmamk_f32 v190, v66, 0xba800000, v153
	v_fmamk_f32 v191, v66, 0xba800000, v157
	v_fmac_f32_e32 v156, 0xba800000, v66
	v_fmac_f32_e32 v82, 0xba800000, v89
	v_fmac_f32_e32 v72, 0xba800000, v89
	v_mov_b32_e32 v83, v78
	v_pk_mul_f32 v[144:145], v[172:173], v[172:173]
	s_waitcnt lgkmcnt(0)
	v_add_f32_e32 v95, v64, v65
	v_fmac_f32_e32 v152, 0xba800000, v66
	v_fmac_f32_e32 v140, 0xba800000, v66
	v_mov_b32_e32 v153, v156
	v_pk_mul_f32 v[64:65], v[190:191], v[190:191]
	v_fmamk_f32 v187, v66, 0xba800000, v149
	v_fmac_f32_e32 v148, 0xba800000, v66
	v_fmamk_f32 v186, v66, 0xba800000, v143
	v_fmamk_f32 v158, v89, 0xba800000, v81
	v_fmac_f32_e32 v80, 0xba800000, v89
	v_pk_fma_f32 v[144:145], v[82:83], v[82:83], v[144:145]
	v_mov_b32_e32 v81, v72
	v_fmamk_f32 v161, v89, 0xba800000, v75
	v_fmac_f32_e32 v74, 0xba800000, v89
	v_fmamk_f32 v160, v89, 0xba800000, v77
	v_fmamk_f32 v184, v66, 0xba800000, v151
	v_fmac_f32_e32 v150, 0xba800000, v66
	v_fmamk_f32 v185, v66, 0xba800000, v141
	v_pk_fma_f32 v[64:65], v[152:153], v[152:153], v[64:65]
	v_mov_b32_e32 v151, v140
	v_fmamk_f32 v171, v66, 0xba800000, v147
	v_fmac_f32_e32 v146, 0xba800000, v66
	v_fmamk_f32 v170, v66, 0xba800000, v139
	v_fmac_f32_e32 v138, 0xba800000, v66
	v_fmac_f32_e32 v142, 0xba800000, v66
	v_mov_b32_e32 v143, v148
	v_pk_mul_f32 v[66:67], v[186:187], v[186:187]
	v_fmamk_f32 v159, v89, 0xba800000, v73
	v_pk_fma_f32 v[144:145], v[80:81], v[80:81], v[144:145]
	v_fmac_f32_e32 v70, 0xba800000, v89
	v_fmac_f32_e32 v76, 0xba800000, v89
	v_mov_b32_e32 v77, v74
	v_pk_mul_f32 v[198:199], v[160:161], v[160:161]
	v_pk_fma_f32 v[64:65], v[150:151], v[150:151], v[64:65]
	v_pk_fma_f32 v[66:67], v[142:143], v[142:143], v[66:67]
	v_mov_b32_e32 v139, v146
	v_pk_fma_f32 v[196:197], v[158:159], v[158:159], v[144:145]
	v_fmamk_f32 v144, v89, 0xba800000, v69
	v_fmac_f32_e32 v68, 0xba800000, v89
	v_pk_fma_f32 v[198:199], v[76:77], v[76:77], v[198:199]
	v_mov_b32_e32 v69, v70
	v_pk_fma_f32 v[64:65], v[184:185], v[184:185], v[64:65]
	v_pk_fma_f32 v[66:67], v[138:139], v[138:139], v[66:67]
	v_fmamk_f32 v145, v89, 0xba800000, v71
	v_pk_fma_f32 v[198:199], v[68:69], v[68:69], v[198:199]
	v_pk_fma_f32 v[66:67], v[170:171], v[170:171], v[66:67]
	v_pk_fma_f32 v[198:199], v[144:145], v[144:145], v[198:199]
	v_mov_b32_e32 v200, v196
	v_mov_b32_e32 v201, v64
	v_mov_b32_e32 v64, v197
	v_pk_add_f32 v[64:65], v[200:201], v[64:65]
	v_mov_b32_e32 v196, v199
	v_mov_b32_e32 v197, v67
	v_pk_add_f32 v[64:65], v[196:197], v[64:65]
	v_mov_b32_e32 v199, v66
	v_pk_add_f32 v[64:65], v[198:199], v[64:65]
	v_mov_b32_e32 v67, v65
	v_mov_b32_e32 v212, v65
	s_mov_b32 s100, 0
	s_mov_b32 s101, -1
	v_permlane32_swap_b32_e32 v67, v212
	v_cndmask_b32_e64 v67, v212, v67, s[100:101]
	v_mov_b32_e32 v66, v64
	v_mov_b32_e32 v212, v64
	s_mov_b32 s100, 0
	s_mov_b32 s101, -1
	v_permlane32_swap_b32_e32 v66, v212
	v_cndmask_b32_e64 v66, v212, v66, s[100:101]
	s_nop 1
	v_mov_b32_dpp v103, v95 row_ror:4 row_mask:0xf bank_mask:0xf
	s_waitcnt lgkmcnt(1)
; DI unsigned cvt_pk_bf16(float lo, float hi) { unsigned r; asm volatile("v_cvt_pk_bf16_f32 %0, %1, %2" : "=v"(r) : "v"(lo), "v"(hi)); return r; }
; template <int NR>
; DI void ln_rows(const Args& a, int l, int row0, int lane, const f32x4 (&lgv)[4], const f32x4 (&lbv)[4], const f32x4 (&gate)[4], const f32x4 (&sh)[4], const f32x4 (&sc1)[4]) {
;     ...
;         rstd[k] = rsqrtf(wave_sum(q) * (1.f / 1024.f) + 1e-5f); }
; #pragma unroll
;     for (int k = 0; k < NR; ++k) { const int row = row0 + k;
;         float* zr = row < TL ? a.out + (size_t)row * 1024 : zc + (size_t)(row - TL) * 1024;
; #pragma unroll
;         for (int i = 0; i < 4; ++i) { const int col = 4 * lane + 256 * i;
;             const f32x4 yo = v[k][i] * rstd[k] * lgv[i] + lbv[i];
;             *(f32x4*)(zr + col) = yo;
;             if (l < 3) { const f32x4 hv = yo * sc1[i] + sh[i]; u32x2 w = {cvt_pk_bf16(hv[0], hv[1]), cvt_pk_bf16(hv[2], hv[3])}; *(u32x2*)(h + (size_t)row * 1024 + col) = w; } } }
	v_pk_add_f32 v[64:65], v[64:65], v[66:67]
	v_mov_b32_e32 v67, v65
	v_mov_b32_e32 v212, v65
	s_mov_b32 s100, 0xffff0000
	s_mov_b32 s101, 0xffff0000
	v_permlane16_swap_b32_e32 v67, v212
	v_cndmask_b32_e64 v67, v212, v67, s[100:101]
	v_mov_b32_e32 v66, v64
	v_mov_b32_e32 v212, v64
	s_mov_b32 s100, 0xffff0000
	s_mov_b32 s101, 0xffff0000
	v_permlane16_swap_b32_e32 v66, v212
	v_cndmask_b32_e64 v66, v212, v66, s[100:101]
	s_waitcnt lgkmcnt(2)
	v_add_f32_e32 v69, v95, v103
	s_nop 1
	v_mov_b32_dpp v71, v69 quad_perm:[2,3,0,1] row_mask:0xf bank_mask:0xf
	s_waitcnt lgkmcnt(1)
	v_pk_add_f32 v[64:65], v[64:65], v[66:67]
	s_nop 1
	v_mov_b32_dpp v67, v65 row_ror:8 row_mask:0xf bank_mask:0xf
	s_nop 1
	v_mov_b32_dpp v66, v64 row_ror:8 row_mask:0xf bank_mask:0xf
	s_waitcnt lgkmcnt(2)
	v_add_f32_e32 v69, v69, v71
	s_nop 1
	v_mov_b32_dpp v71, v69 quad_perm:[1,0,3,2] row_mask:0xf bank_mask:0xf
	s_waitcnt lgkmcnt(1)
	v_pk_add_f32 v[64:65], v[64:65], v[66:67]
	s_nop 1
	v_mov_b32_dpp v67, v65 row_ror:4 row_mask:0xf bank_mask:0xf
	s_nop 1
	v_mov_b32_dpp v66, v64 row_ror:4 row_mask:0xf bank_mask:0xf
	s_waitcnt lgkmcnt(2)
	v_add_f32_e32 v69, v69, v71
	v_fmamk_f32 v69, v69, 0x3a800000, v182
	v_mul_f32_e32 v71, 0x4b800000, v69
	v_cmp_gt_f32_e32 vcc, s94, v69
	s_waitcnt lgkmcnt(0)
	v_pk_add_f32 v[64:65], v[64:65], v[66:67]
	s_nop 1
	v_mov_b32_dpp v67, v65 quad_perm:[2,3,0,1] row_mask:0xf bank_mask:0xf
	s_nop 1
	v_mov_b32_dpp v66, v64 quad_perm:[2,3,0,1] row_mask:0xf bank_mask:0xf
	v_cndmask_b32_e32 v69, v69, v71, vcc
	v_rsq_f32_e32 v69, v69
	s_waitcnt lgkmcnt(0)
	v_pk_add_f32 v[196:197], v[64:65], v[66:67]
	v_mul_f32_e32 v71, 0x45800000, v69
	s_nop 1
	v_mov_b32_dpp v199, v197 quad_perm:[1,0,3,2] row_mask:0xf bank_mask:0xf
	s_nop 1
	v_mov_b32_dpp v198, v196 quad_perm:[1,0,3,2] row_mask:0xf bank_mask:0xf
	v_cndmask_b32_e32 v200, v69, v71, vcc
	v_mov_b32_e32 v201, v200
	v_pk_mul_f32 v[64:65], v[178:179], v[200:201] op_sel_hi:[1,0]
	v_pk_mul_f32 v[66:67], v[176:177], v[200:201] op_sel_hi:[1,0]
	v_cndmask_b32_e64 v69, 0, 1, s[16:17]
	v_pk_fma_f32 v[66:67], v[2:3], v[66:67], v[10:11]
	v_pk_fma_f32 v[64:65], v[0:1], v[64:65], v[8:9]
	v_cmp_ne_u32_e64 s[0:1], 1, v69
	s_andn2_b64 vcc, exec, s[16:17]
	v_pk_mul_f32 v[174:175], v[174:175], v[200:201]
	global_store_dwordx4 v[128:129], v[64:67], off offset:-3072 nt
	s_cbranch_vccnz .LBB0_977
	s_nop 0
	v_pk_fma_f32 v[66:67], v[122:123], v[66:67], v[42:43]
	v_pk_fma_f32 v[64:65], v[120:121], v[64:65], v[40:41]
	v_mov_b32_e32 v169, v193
	v_cvt_pk_bf16_f32 v64, v64, v65
	v_cvt_pk_bf16_f32 v65, v66, v67
	v_add_co_u32_e32 v66, vcc, 0xfbc00000, v124
	s_mov_b64 s[8:9], 0
	s_nop 0
	v_addc_co_u32_e32 v67, vcc, -1, v125, vcc
	global_store_dwordx2 v[66:67], v[64:65], off
	v_mov_b32_e32 v64, v200
	v_mov_b32_e32 v65, v200
	v_pk_mul_f32 v[64:65], v[168:169], v[64:65]
	s_nop 0
	v_pk_fma_f32 v[66:67], v[6:7], v[64:65], v[14:15]
	v_pk_fma_f32 v[64:65], v[4:5], v[174:175], v[12:13]
	global_store_dwordx4 v[128:129], v[64:67], off offset:-2048 nt
	s_nop 1
	v_pk_fma_f32 v[66:67], v[118:119], v[66:67], v[46:47]
	v_pk_fma_f32 v[64:65], v[116:117], v[64:65], v[44:45]
	s_nop 0
	v_cvt_pk_bf16_f32 v64, v64, v65
	v_cvt_pk_bf16_f32 v65, v66, v67
	v_add_co_u32_e32 v66, vcc, 0xfbc01000, v124
	s_nop 1
	v_addc_co_u32_e32 v67, vcc, -1, v125, vcc
	global_store_dwordx2 v[66:67], v[64:65], off offset:-3584

; DI float bflo(unsigned w) { return __uint_as_float(w << 16); }
; DI float bfhi(unsigned w) { return __uint_as_float(w & 0xffff0000u); }
; template <int NR>
; DI void ln_rows(const Args& a, int l, int row0, int lane, const f32x4 (&lgv)[4], const f32x4 (&lbv)[4], const f32x4 (&gate)[4], const f32x4 (&sh)[4], const f32x4 (&sc1)[4]) {
;     ...
;     for (int k = 0; k < NR; ++k) { const int row = row0 + k; s[k] = 0.f;
;         const float* xr = row < TL ? xlat + (size_t)row * 1024 : xctx + (size_t)(row - TL) * 1024;
; #pragma unroll
;         for (int i = 0; i < 4; ++i) { const int col = 4 * lane + 256 * i;
;             const f32x4 xv = *(const f32x4*)(xr + col); const u32x2 yw = *(const u32x2*)(y + (size_t)row * 1024 + col);
;             f32x4 yv; yv[0] = bflo(yw[0]); yv[1] = bfhi(yw[0]); yv[2] = bflo(yw[1]); yv[3] = bfhi(yw[1]);
;             v[k][i] = xv * ALPHA + gate[i] * yv; s[k] += v[k][i][0] + v[k][i][1] + v[k][i][2] + v[k][i][3]; } }
;     float mean[NR], rstd[NR];
; #pragma unroll
;     for (int k = 0; k < NR; ++k) mean[k] = wave_sum(s[k]) * (1.f / 1024.f);
.LBB0_999:
	v_lshlrev_b32_e32 v64, 4, v211
	v_or_b32_e32 v68, 15, v64
	s_mov_b32 s6, 0x8000
	v_add_u32_e32 v64, 0xffff800f, v64
	v_mov_b32_e32 v65, v181
	v_ashrrev_i32_e32 v69, 31, v68
	v_cmp_gt_i32_e32 vcc, s6, v68
	v_lshlrev_b64 v[64:65], 12, v[64:65]
	v_lshlrev_b64 v[66:67], 12, v[68:69]
	v_lshlrev_b64 v[68:69], 11, v[68:69]
	v_lshl_add_u64 v[70:71], s[20:21], 0, v[64:65]
	v_lshl_add_u64 v[72:73], s[18:19], 0, v[66:67]
	v_lshl_add_u64 v[76:77], v[90:91], 0, v[68:69]
	v_cndmask_b32_e32 v71, v71, v73, vcc
	v_cndmask_b32_e32 v70, v70, v72, vcc
	global_load_dwordx2 v[78:79], v[76:77], off nt
	v_lshl_add_u64 v[74:75], v[70:71], 0, v[180:181]
	global_load_dwordx4 v[70:73], v[74:75], off nt
	s_waitcnt vmcnt(1)
	v_lshlrev_b32_e32 v80, 16, v78
	v_and_b32_e32 v81, 0xffff0000, v78
	v_lshlrev_b32_e32 v78, 16, v79
	v_and_b32_e32 v79, 0xffff0000, v79
	v_pk_mul_f32 v[80:81], v[60:61], v[80:81]
	v_pk_mul_f32 v[60:61], v[62:63], v[78:79]
	s_waitcnt vmcnt(0)
	v_pk_fma_f32 v[62:63], v[70:71], s[44:45], v[80:81] op_sel_hi:[1,0,1]
	v_pk_fma_f32 v[60:61], v[72:73], s[44:45], v[60:61] op_sel_hi:[1,0,1]
	global_load_dwordx4 v[70:73], v[74:75], off offset:1024 nt
	global_load_dwordx2 v[78:79], v[76:77], off offset:512 nt
	s_waitcnt vmcnt(0)
	v_lshlrev_b32_e32 v80, 16, v78
	v_and_b32_e32 v81, 0xffff0000, v78
	v_lshlrev_b32_e32 v78, 16, v79
	v_and_b32_e32 v79, 0xffff0000, v79
	v_pk_mul_f32 v[80:81], v[56:57], v[80:81]
	v_pk_mul_f32 v[56:57], v[58:59], v[78:79]
	v_pk_fma_f32 v[58:59], v[70:71], s[44:45], v[80:81] op_sel_hi:[1,0,1]
	v_pk_fma_f32 v[56:57], v[72:73], s[44:45], v[56:57] op_sel_hi:[1,0,1]
	v_mov_b32_e32 v70, v62
	v_mov_b32_e32 v71, v58
	v_mov_b32_e32 v72, v63
	v_mov_b32_e32 v73, v59
	v_pk_add_f32 v[70:71], v[70:71], v[72:73]
	v_mov_b32_e32 v72, v60
	v_mov_b32_e32 v73, v56
	v_pk_add_f32 v[70:71], v[72:73], v[70:71]
	v_mov_b32_e32 v72, v61
	v_mov_b32_e32 v73, v57
	v_pk_add_f32 v[70:71], v[72:73], v[70:71]
	s_nop 0
	v_add_f32_e32 v70, 0, v70
	v_add_f32_e32 v82, v70, v71
	global_load_dwordx4 v[70:73], v[74:75], off offset:2048 nt
	global_load_dwordx2 v[78:79], v[76:77], off offset:1024 nt
	s_waitcnt vmcnt(0)
	v_lshlrev_b32_e32 v80, 16, v78
	v_and_b32_e32 v81, 0xffff0000, v78
	v_lshlrev_b32_e32 v78, 16, v79
	v_and_b32_e32 v79, 0xffff0000, v79
	v_pk_mul_f32 v[80:81], v[52:53], v[80:81]
	v_pk_mul_f32 v[52:53], v[54:55], v[78:79]
	v_pk_fma_f32 v[54:55], v[70:71], s[44:45], v[80:81] op_sel_hi:[1,0,1]
	v_pk_fma_f32 v[52:53], v[72:73], s[44:45], v[52:53] op_sel_hi:[1,0,1]
	global_load_dwordx4 v[72:75], v[74:75], off offset:3072 nt
	s_nop 0
	global_load_dwordx2 v[70:71], v[76:77], off offset:1536 nt
	s_waitcnt vmcnt(0)
	v_lshlrev_b32_e32 v76, 16, v70
	v_and_b32_e32 v77, 0xffff0000, v70
	v_lshlrev_b32_e32 v70, 16, v71
	v_and_b32_e32 v71, 0xffff0000, v71
	v_pk_mul_f32 v[48:49], v[48:49], v[76:77]
	v_pk_mul_f32 v[50:51], v[50:51], v[70:71]
	v_pk_fma_f32 v[72:73], v[72:73], s[44:45], v[48:49] op_sel_hi:[1,0,1]
	v_pk_fma_f32 v[70:71], v[74:75], s[44:45], v[50:51] op_sel_hi:[1,0,1]
	v_mov_b32_e32 v48, v54
	v_mov_b32_e32 v49, v72
	v_mov_b32_e32 v50, v55
	v_mov_b32_e32 v51, v73
	v_pk_add_f32 v[48:49], v[48:49], v[50:51]
	v_mov_b32_e32 v50, v52
	v_mov_b32_e32 v51, v70
	v_pk_add_f32 v[48:49], v[50:51], v[48:49]
	v_mov_b32_e32 v50, v53
	v_mov_b32_e32 v51, v71
	v_pk_add_f32 v[48:49], v[50:51], v[48:49]
	s_nop 0
	v_add_f32_e32 v48, v82, v48
	v_add_f32_e32 v48, v48, v49
	v_mov_b32_e32 v49, v48
	v_mov_b32_e32 v212, v48
	s_mov_b32 s100, 0
	s_mov_b32 s101, -1
	v_permlane32_swap_b32_e32 v49, v212
	v_cndmask_b32_e64 v49, v212, v49, s[100:101]
	s_waitcnt lgkmcnt(0)
	v_add_f32_e32 v48, v48, v49
	v_mov_b32_e32 v49, v48
	v_mov_b32_e32 v212, v48
	s_mov_b32 s100, 0xffff0000
	s_mov_b32 s101, 0xffff0000
	v_permlane16_swap_b32_e32 v49, v212
	v_cndmask_b32_e64 v49, v212, v49, s[100:101]
	s_waitcnt lgkmcnt(0)
	v_add_f32_e32 v48, v48, v49
	s_nop 1
	v_mov_b32_dpp v49, v48 row_ror:8 row_mask:0xf bank_mask:0xf
	s_waitcnt lgkmcnt(0)
	v_add_f32_e32 v48, v48, v49
	s_nop 1
	v_mov_b32_dpp v49, v48 row_ror:4 row_mask:0xf bank_mask:0xf
	s_waitcnt lgkmcnt(0)
	v_add_f32_e32 v48, v48, v49
	s_nop 1
	v_mov_b32_dpp v49, v48 quad_perm:[2,3,0,1] row_mask:0xf bank_mask:0xf
	s_waitcnt lgkmcnt(0)
	v_add_f32_e32 v48, v48, v49
	s_nop 1
	v_mov_b32_dpp v49, v48 quad_perm:[1,0,3,2] row_mask:0xf bank_mask:0xf
	s_waitcnt lgkmcnt(0)
; DI unsigned cvt_pk_bf16(float lo, float hi) { unsigned r; asm volatile("v_cvt_pk_bf16_f32 %0, %1, %2" : "=v"(r) : "v"(lo), "v"(hi)); return r; }
; template <int NR>
; DI void ln_rows(const Args& a, int l, int row0, int lane, const f32x4 (&lgv)[4], const f32x4 (&lbv)[4], const f32x4 (&gate)[4], const f32x4 (&sh)[4], const f32x4 (&sc1)[4]) {
;     ...
;     for (int k = 0; k < NR; ++k) mean[k] = wave_sum(s[k]) * (1.f / 1024.f);
; #pragma unroll
;     for (int k = 0; k < NR; ++k) { float q = 0.f;
; #pragma unroll
;         for (int i = 0; i < 4; ++i) { v[k][i] = v[k][i] - mean[k]; q += v[k][i][0] * v[k][i][0] + v[k][i][1] * v[k][i][1] + v[k][i][2] * v[k][i][2] + v[k][i][3] * v[k][i][3]; }
;         rstd[k] = rsqrtf(wave_sum(q) * (1.f / 1024.f) + 1e-5f); }
; #pragma unroll
;     for (int k = 0; k < NR; ++k) { const int row = row0 + k;
;         float* zr = row < TL ? a.out + (size_t)row * 1024 : zc + (size_t)(row - TL) * 1024;
; #pragma unroll
;         for (int i = 0; i < 4; ++i) { const int col = 4 * lane + 256 * i;
;             const f32x4 yo = v[k][i] * rstd[k] * lgv[i] + lbv[i];
;             *(f32x4*)(zr + col) = yo;
;             if (l < 3) { const f32x4 hv = yo * sc1[i] + sh[i]; u32x2 w = {cvt_pk_bf16(hv[0], hv[1]), cvt_pk_bf16(hv[2], hv[3])}; *(u32x2*)(h + (size_t)row * 1024 + col) = w; } } }
	v_add_f32_e32 v75, v48, v49
	v_fmamk_f32 v63, v75, 0xba800000, v63
	v_fmamk_f32 v59, v75, 0xba800000, v59
	v_fmac_f32_e32 v62, 0xba800000, v75
	v_fmac_f32_e32 v58, 0xba800000, v75
	v_mov_b32_e32 v50, v63
	v_mov_b32_e32 v51, v59
	v_fmac_f32_e32 v60, 0xba800000, v75
	v_fmac_f32_e32 v56, 0xba800000, v75
	v_mov_b32_e32 v48, v62
	v_mov_b32_e32 v49, v58
	v_pk_mul_f32 v[50:51], v[50:51], v[50:51]
	v_fmamk_f32 v55, v75, 0xba800000, v55
	v_fmamk_f32 v73, v75, 0xba800000, v73
	v_pk_fma_f32 v[48:49], v[48:49], v[48:49], v[50:51]
	v_mov_b32_e32 v50, v60
	v_mov_b32_e32 v51, v56
	v_fmac_f32_e32 v54, 0xba800000, v75
	v_fmac_f32_e32 v72, 0xba800000, v75
	v_mov_b32_e32 v78, v73
	v_mov_b32_e32 v79, v55
	v_fmamk_f32 v61, v75, 0xba800000, v61
	v_pk_fma_f32 v[48:49], v[50:51], v[50:51], v[48:49]
	v_fmac_f32_e32 v52, 0xba800000, v75
	v_mov_b32_e32 v50, v72
	v_mov_b32_e32 v51, v54
	v_pk_mul_f32 v[78:79], v[78:79], v[78:79]
	v_fmamk_f32 v77, v75, 0xba800000, v57
	v_mov_b32_e32 v76, v61
	v_fmamk_f32 v53, v75, 0xba800000, v53
	v_fmamk_f32 v74, v75, 0xba800000, v71
	v_fmac_f32_e32 v70, 0xba800000, v75
	v_pk_fma_f32 v[50:51], v[50:51], v[50:51], v[78:79]
	v_mov_b32_e32 v71, v52
	v_pk_fma_f32 v[48:49], v[76:77], v[76:77], v[48:49]
	v_pk_fma_f32 v[50:51], v[70:71], v[70:71], v[50:51]
	v_mov_b32_e32 v75, v53
	v_pk_fma_f32 v[50:51], v[74:75], v[74:75], v[50:51]
	v_add_f32_e32 v48, v48, v49
	v_add_f32_e32 v48, v51, v48
	v_add_f32_e32 v48, v50, v48
	v_mov_b32_e32 v49, v48
	v_mov_b32_e32 v212, v48
	s_mov_b32 s100, 0
	s_mov_b32 s101, -1
	v_permlane32_swap_b32_e32 v49, v212
	v_cndmask_b32_e64 v49, v212, v49, s[100:101]
	v_lshl_add_u64 v[50:51], s[26:27], 0, v[66:67]
	s_waitcnt lgkmcnt(0)
	v_add_f32_e32 v48, v48, v49
	v_mov_b32_e32 v49, v48
	v_mov_b32_e32 v212, v48
	s_mov_b32 s100, 0xffff0000
	s_mov_b32 s101, 0xffff0000
	v_permlane16_swap_b32_e32 v49, v212
	v_cndmask_b32_e64 v49, v212, v49, s[100:101]
	s_waitcnt lgkmcnt(0)
	v_add_f32_e32 v48, v48, v49
	s_nop 1
	v_mov_b32_dpp v49, v48 row_ror:8 row_mask:0xf bank_mask:0xf
	s_waitcnt lgkmcnt(0)
	v_add_f32_e32 v48, v48, v49
	s_nop 1
	v_mov_b32_dpp v49, v48 row_ror:4 row_mask:0xf bank_mask:0xf
	s_waitcnt lgkmcnt(0)
	v_add_f32_e32 v48, v48, v49
	s_nop 1
	v_mov_b32_dpp v49, v48 quad_perm:[2,3,0,1] row_mask:0xf bank_mask:0xf
	s_waitcnt lgkmcnt(0)
	v_add_f32_e32 v48, v48, v49
	s_nop 1
	v_mov_b32_dpp v49, v48 quad_perm:[1,0,3,2] row_mask:0xf bank_mask:0xf
	s_waitcnt lgkmcnt(0)
	v_add_f32_e32 v48, v48, v49
	v_fmamk_f32 v48, v48, 0x3a800000, v182
	v_cmp_gt_f32_e64 s[6:7], s94, v48
	v_mul_f32_e32 v49, 0x4b800000, v48
	s_nop 0
	v_cndmask_b32_e64 v48, v48, v49, s[6:7]
	v_rsq_f32_e32 v48, v48
	s_nop 0
	v_mul_f32_e32 v49, 0x45800000, v48
	v_cndmask_b32_e64 v78, v48, v49, s[6:7]
	v_lshl_add_u64 v[48:49], s[84:85], 0, v[64:65]
	v_mov_b32_e32 v80, v78
	v_mov_b32_e32 v81, v78
	v_cndmask_b32_e32 v67, v49, v51, vcc
	v_cndmask_b32_e32 v66, v48, v50, vcc
	v_pk_mul_f32 v[48:49], v[62:63], v[78:79] op_sel_hi:[1,0]
	v_pk_mul_f32 v[50:51], v[60:61], v[78:79] op_sel_hi:[1,0]
	v_lshl_add_u64 v[64:65], s[90:91], 0, v[68:69]
	v_pk_fma_f32 v[50:51], v[2:3], v[50:51], v[10:11]
	v_pk_fma_f32 v[48:49], v[0:1], v[48:49], v[8:9]
	v_lshl_add_u64 v[60:61], v[66:67], 0, v[180:181]
	s_mov_b64 s[6:7], -1
	s_and_b64 vcc, exec, s[0:1]
	v_pk_mul_f32 v[58:59], v[58:59], v[80:81]
	global_store_dwordx4 v[60:61], v[48:51], off nt
	s_cbranch_vccnz .LBB0_1001
	v_pk_fma_f32 v[40:41], v[120:121], v[48:49], v[40:41]
	v_mov_b32_e32 v89, v181
	v_pk_fma_f32 v[42:43], v[122:123], v[50:51], v[42:43]
	v_cvt_pk_bf16_f32 v40, v40, v41
	v_lshl_add_u64 v[48:49], v[64:65], 0, v[88:89]
	v_cvt_pk_bf16_f32 v41, v42, v43
	v_mov_b32_e32 v79, v78
	v_mov_b32_e32 v57, v77
	global_store_dwordx2 v[48:49], v[40:41], off
	v_pk_mul_f32 v[40:41], v[56:57], v[78:79]
	s_mov_b64 s[6:7], 0
	v_pk_fma_f32 v[42:43], v[6:7], v[40:41], v[14:15]
	v_pk_fma_f32 v[40:41], v[4:5], v[58:59], v[12:13]
	global_store_dwordx4 v[60:61], v[40:43], off offset:1024 nt
	s_nop 1
	v_pk_fma_f32 v[40:41], v[116:117], v[40:41], v[44:45]
	v_pk_fma_f32 v[42:43], v[118:119], v[42:43], v[46:47]
	v_cvt_pk_bf16_f32 v40, v40, v41
	s_nop 0
	v_cvt_pk_bf16_f32 v41, v42, v43
	global_store_dwordx2 v[48:49], v[40:41], off offset:512

; DI float bflo(unsigned w) { return __uint_as_float(w << 16); }
; DI float bfhi(unsigned w) { return __uint_as_float(w & 0xffff0000u); }
; template <int NR>
; DI void ln_rows(const Args& a, int l, int row0, int lane, const f32x4 (&lgv)[4], const f32x4 (&lbv)[4], const f32x4 (&gate)[4], const f32x4 (&sh)[4], const f32x4 (&sc1)[4]) {
;     ...
;     for (int k = 0; k < NR; ++k) { const int row = row0 + k; s[k] = 0.f;
;         const float* xr = row < TL ? xlat + (size_t)row * 1024 : xctx + (size_t)(row - TL) * 1024;
; #pragma unroll
;         for (int i = 0; i < 4; ++i) { const int col = 4 * lane + 256 * i;
;             const f32x4 xv = *(const f32x4*)(xr + col); const u32x2 yw = *(const u32x2*)(y + (size_t)row * 1024 + col);
;             f32x4 yv; yv[0] = bflo(yw[0]); yv[1] = bfhi(yw[0]); yv[2] = bflo(yw[1]); yv[3] = bfhi(yw[1]);
;             v[k][i] = xv * ALPHA + gate[i] * yv; s[k] += v[k][i][0] + v[k][i][1] + v[k][i][2] + v[k][i][3]; } }
;     float mean[NR], rstd[NR];
; #pragma unroll
;     for (int k = 0; k < NR; ++k) mean[k] = wave_sum(s[k]) * (1.f / 1024.f);
.LBB0_1010:
	v_add_u32_e32 v88, 0x8000, v84
	v_mov_b32_e32 v85, v181
	v_ashrrev_i32_e32 v89, 31, v88
	v_lshlrev_b64 v[90:91], 12, v[84:85]
	v_lshlrev_b64 v[92:93], 12, v[88:89]
	v_lshlrev_b64 v[100:101], 11, v[88:89]
	v_lshl_add_u64 v[86:87], s[6:7], 0, v[90:91]
	v_lshl_add_u64 v[88:89], s[84:85], 0, v[90:91]
	v_lshl_add_u64 v[90:91], s[4:5], 0, v[92:93]
	v_cmp_gt_i32_e32 vcc, 0, v84
	v_lshl_add_u64 v[102:103], v[80:81], 0, v[100:101]
	v_lshl_add_u64 v[104:105], s[26:27], 0, v[92:93]
	global_load_dwordx2 v[112:113], v[102:103], off nt
	global_load_dwordx2 v[114:115], v[102:103], off offset:512 nt
	global_load_dwordx2 v[116:117], v[102:103], off offset:1024 nt
	global_load_dwordx2 v[118:119], v[102:103], off offset:1536 nt
	v_cndmask_b32_e32 v87, v87, v91, vcc
	v_cndmask_b32_e32 v86, v86, v90, vcc
	v_cndmask_b32_e32 v89, v89, v105, vcc
	v_cndmask_b32_e32 v88, v88, v104, vcc
	v_lshl_add_u64 v[90:91], v[86:87], 0, v[180:181]
	v_lshl_add_u64 v[92:93], v[82:83], 0, v[100:101]
	v_lshl_add_u64 v[120:121], v[88:89], 0, v[180:181]
	global_load_dwordx4 v[86:89], v[90:91], off nt
	global_load_dwordx4 v[100:103], v[90:91], off offset:1024 nt
	global_load_dwordx4 v[104:107], v[90:91], off offset:2048 nt
	global_load_dwordx4 v[108:111], v[90:91], off offset:3072 nt
	v_add_u32_e32 v84, s45, v84
	v_cmp_lt_i32_e32 vcc, s46, v84
	s_or_b64 s[8:9], vcc, s[8:9]
	s_waitcnt vmcnt(7)
	v_lshlrev_b32_e32 v90, 16, v112
	v_and_b32_e32 v91, 0xffff0000, v112
	s_waitcnt vmcnt(6)
	v_lshlrev_b32_e32 v122, 16, v114
	v_and_b32_e32 v123, 0xffff0000, v114
	v_lshlrev_b32_e32 v112, 16, v113
	v_and_b32_e32 v113, 0xffff0000, v113
	v_lshlrev_b32_e32 v114, 16, v115
	v_and_b32_e32 v115, 0xffff0000, v115
	s_waitcnt vmcnt(5)
	v_lshlrev_b32_e32 v124, 16, v116
	v_and_b32_e32 v125, 0xffff0000, v116
	v_lshlrev_b32_e32 v116, 16, v117
	v_and_b32_e32 v117, 0xffff0000, v117
	s_waitcnt vmcnt(4)
	v_lshlrev_b32_e32 v126, 16, v118
	v_and_b32_e32 v127, 0xffff0000, v118
	v_lshlrev_b32_e32 v118, 16, v119
	v_and_b32_e32 v119, 0xffff0000, v119
	v_pk_mul_f32 v[90:91], v[32:33], v[90:91]
	v_pk_mul_f32 v[122:123], v[40:41], v[122:123]
	v_pk_mul_f32 v[112:113], v[34:35], v[112:113]
	v_pk_mul_f32 v[114:115], v[42:43], v[114:115]
	v_pk_mul_f32 v[116:117], v[50:51], v[116:117]
	v_pk_mul_f32 v[118:119], v[58:59], v[118:119]
	s_waitcnt vmcnt(3)
	v_pk_fma_f32 v[86:87], v[86:87], s[44:45], v[90:91] op_sel_hi:[1,0,1]
	s_waitcnt vmcnt(2)
	v_pk_fma_f32 v[100:101], v[100:101], s[44:45], v[122:123] op_sel_hi:[1,0,1]
	v_pk_mul_f32 v[124:125], v[48:49], v[124:125]
	v_pk_mul_f32 v[126:127], v[56:57], v[126:127]
	v_pk_fma_f32 v[88:89], v[88:89], s[44:45], v[112:113] op_sel_hi:[1,0,1]
	v_pk_fma_f32 v[90:91], v[102:103], s[44:45], v[114:115] op_sel_hi:[1,0,1]
	s_waitcnt vmcnt(1)
	v_pk_fma_f32 v[102:103], v[106:107], s[44:45], v[116:117] op_sel_hi:[1,0,1]
	s_waitcnt vmcnt(0)
	v_pk_fma_f32 v[106:107], v[110:111], s[44:45], v[118:119] op_sel_hi:[1,0,1]
	v_mov_b32_e32 v110, v86
	v_mov_b32_e32 v111, v100
	v_mov_b32_e32 v112, v87
	v_mov_b32_e32 v113, v101
	v_pk_fma_f32 v[104:105], v[104:105], s[44:45], v[124:125] op_sel_hi:[1,0,1]
	v_pk_fma_f32 v[108:109], v[108:109], s[44:45], v[126:127] op_sel_hi:[1,0,1]
	v_mov_b32_e32 v114, v88
	v_mov_b32_e32 v115, v90
	v_pk_add_f32 v[110:111], v[110:111], v[112:113]
	v_mov_b32_e32 v116, v89
	v_mov_b32_e32 v117, v91
	v_mov_b32_e32 v118, v104
	v_mov_b32_e32 v119, v108
	v_mov_b32_e32 v122, v105
	v_mov_b32_e32 v123, v109
	v_pk_add_f32 v[110:111], v[114:115], v[110:111]
	v_mov_b32_e32 v124, v102
	v_mov_b32_e32 v125, v106
	v_pk_add_f32 v[112:113], v[118:119], v[122:123]
	v_pk_add_f32 v[110:111], v[116:117], v[110:111]
	v_mov_b32_e32 v126, v103
	v_mov_b32_e32 v127, v107
	v_pk_add_f32 v[112:113], v[124:125], v[112:113]
	v_add_f32_e32 v85, 0, v110
	v_pk_add_f32 v[112:113], v[126:127], v[112:113]
	v_add_f32_e32 v85, v85, v111
	v_add_f32_e32 v85, v85, v112
	v_add_f32_e32 v85, v85, v113
	v_mov_b32_e32 v110, v85
	v_mov_b32_e32 v212, v85
	s_mov_b32 s100, 0
	s_mov_b32 s101, -1
	v_permlane32_swap_b32_e32 v110, v212
	v_cndmask_b32_e64 v110, v212, v110, s[100:101]
	s_waitcnt lgkmcnt(0)
	v_add_f32_e32 v85, v85, v110
	v_mov_b32_e32 v110, v85
	v_mov_b32_e32 v212, v85
	s_mov_b32 s100, 0xffff0000
	s_mov_b32 s101, 0xffff0000
	v_permlane16_swap_b32_e32 v110, v212
	v_cndmask_b32_e64 v110, v212, v110, s[100:101]
	s_waitcnt lgkmcnt(0)
	v_add_f32_e32 v85, v85, v110
	s_nop 1
	v_mov_b32_dpp v110, v85 row_ror:8 row_mask:0xf bank_mask:0xf
	s_waitcnt lgkmcnt(0)
	v_add_f32_e32 v85, v85, v110
	s_nop 1
	v_mov_b32_dpp v110, v85 row_ror:4 row_mask:0xf bank_mask:0xf
	s_waitcnt lgkmcnt(0)
	v_add_f32_e32 v85, v85, v110
	s_nop 1
	v_mov_b32_dpp v110, v85 quad_perm:[2,3,0,1] row_mask:0xf bank_mask:0xf
	s_waitcnt lgkmcnt(0)
	v_add_f32_e32 v85, v85, v110
	s_nop 1
	v_mov_b32_dpp v110, v85 quad_perm:[1,0,3,2] row_mask:0xf bank_mask:0xf
	s_waitcnt lgkmcnt(0)
; DI unsigned cvt_pk_bf16(float lo, float hi) { unsigned r; asm volatile("v_cvt_pk_bf16_f32 %0, %1, %2" : "=v"(r) : "v"(lo), "v"(hi)); return r; }
; template <int NR>
; DI void ln_rows(const Args& a, int l, int row0, int lane, const f32x4 (&lgv)[4], const f32x4 (&lbv)[4], const f32x4 (&gate)[4], const f32x4 (&sh)[4], const f32x4 (&sc1)[4]) {
;     ...
;     for (int k = 0; k < NR; ++k) mean[k] = wave_sum(s[k]) * (1.f / 1024.f);
; #pragma unroll
;     for (int k = 0; k < NR; ++k) { float q = 0.f;
; #pragma unroll
;         for (int i = 0; i < 4; ++i) { v[k][i] = v[k][i] - mean[k]; q += v[k][i][0] * v[k][i][0] + v[k][i][1] * v[k][i][1] + v[k][i][2] * v[k][i][2] + v[k][i][3] * v[k][i][3]; }
;         rstd[k] = rsqrtf(wave_sum(q) * (1.f / 1024.f) + 1e-5f); }
; #pragma unroll
;     for (int k = 0; k < NR; ++k) { const int row = row0 + k;
;         float* zr = row < TL ? a.out + (size_t)row * 1024 : zc + (size_t)(row - TL) * 1024;
; #pragma unroll
;         for (int i = 0; i < 4; ++i) { const int col = 4 * lane + 256 * i;
;             const f32x4 yo = v[k][i] * rstd[k] * lgv[i] + lbv[i];
;             *(f32x4*)(zr + col) = yo;
;             if (l < 3) { const f32x4 hv = yo * sc1[i] + sh[i]; u32x2 w = {cvt_pk_bf16(hv[0], hv[1]), cvt_pk_bf16(hv[2], hv[3])}; *(u32x2*)(h + (size_t)row * 1024 + col) = w; } } }
	v_add_f32_e32 v85, v85, v110
	v_fmamk_f32 v87, v85, 0xba800000, v87
	v_fmamk_f32 v101, v85, 0xba800000, v101
	v_fmac_f32_e32 v86, 0xba800000, v85
	v_fmac_f32_e32 v100, 0xba800000, v85
	v_fmamk_f32 v105, v85, 0xba800000, v105
	v_fmamk_f32 v109, v85, 0xba800000, v109
	v_mov_b32_e32 v112, v87
	v_mov_b32_e32 v113, v101
	v_fmac_f32_e32 v88, 0xba800000, v85
	v_fmac_f32_e32 v90, 0xba800000, v85
	v_fmac_f32_e32 v104, 0xba800000, v85
	v_fmac_f32_e32 v108, 0xba800000, v85
	v_mov_b32_e32 v110, v86
	v_mov_b32_e32 v111, v100
	v_mov_b32_e32 v122, v109
	v_mov_b32_e32 v123, v105
	v_pk_mul_f32 v[112:113], v[112:113], v[112:113]
	v_fmamk_f32 v89, v85, 0xba800000, v89
	v_fmamk_f32 v91, v85, 0xba800000, v91
	v_fmac_f32_e32 v102, 0xba800000, v85
	v_fmac_f32_e32 v106, 0xba800000, v85
	v_mov_b32_e32 v114, v88
	v_mov_b32_e32 v115, v90
	v_mov_b32_e32 v118, v108
	v_mov_b32_e32 v119, v104
	v_pk_mul_f32 v[122:123], v[122:123], v[122:123]
	v_pk_fma_f32 v[110:111], v[110:111], v[110:111], v[112:113]
	v_fmamk_f32 v103, v85, 0xba800000, v103
	v_fmamk_f32 v107, v85, 0xba800000, v107
	v_mov_b32_e32 v116, v89
	v_mov_b32_e32 v117, v91
	v_mov_b32_e32 v124, v106
	v_mov_b32_e32 v125, v102
	v_pk_fma_f32 v[112:113], v[118:119], v[118:119], v[122:123]
	v_pk_fma_f32 v[110:111], v[114:115], v[114:115], v[110:111]
	v_mov_b32_e32 v126, v107
	v_mov_b32_e32 v127, v103
	v_pk_fma_f32 v[112:113], v[124:125], v[124:125], v[112:113]
	v_pk_fma_f32 v[110:111], v[116:117], v[116:117], v[110:111]
	v_pk_fma_f32 v[112:113], v[126:127], v[126:127], v[112:113]
	v_add_f32_e32 v85, v110, v111
	v_add_f32_e32 v85, v113, v85
	v_add_f32_e32 v85, v112, v85
	v_mov_b32_e32 v110, v85
	v_mov_b32_e32 v212, v85
	s_mov_b32 s100, 0
	s_mov_b32 s101, -1
	v_permlane32_swap_b32_e32 v110, v212
	v_cndmask_b32_e64 v110, v212, v110, s[100:101]
	s_waitcnt lgkmcnt(0)
	v_add_f32_e32 v85, v85, v110
	v_mov_b32_e32 v110, v85
	v_mov_b32_e32 v212, v85
	s_mov_b32 s100, 0xffff0000
	s_mov_b32 s101, 0xffff0000
	v_permlane16_swap_b32_e32 v110, v212
	v_cndmask_b32_e64 v110, v212, v110, s[100:101]
	s_waitcnt lgkmcnt(0)
	v_add_f32_e32 v85, v85, v110
	s_nop 1
	v_mov_b32_dpp v110, v85 row_ror:8 row_mask:0xf bank_mask:0xf
	s_waitcnt lgkmcnt(0)
	v_add_f32_e32 v85, v85, v110
	s_nop 1
	v_mov_b32_dpp v110, v85 row_ror:4 row_mask:0xf bank_mask:0xf
	s_waitcnt lgkmcnt(0)
	v_add_f32_e32 v85, v85, v110
	s_nop 1
	v_mov_b32_dpp v110, v85 quad_perm:[2,3,0,1] row_mask:0xf bank_mask:0xf
	s_waitcnt lgkmcnt(0)
	v_add_f32_e32 v85, v85, v110
	s_nop 1
	v_mov_b32_dpp v110, v85 quad_perm:[1,0,3,2] row_mask:0xf bank_mask:0xf
	s_waitcnt lgkmcnt(0)
	v_add_f32_e32 v85, v85, v110
	v_fmamk_f32 v85, v85, 0x3a800000, v182
	v_mul_f32_e32 v110, 0x4b800000, v85
	v_cmp_gt_f32_e32 vcc, s94, v85
	s_nop 1
	v_cndmask_b32_e32 v85, v85, v110, vcc
	v_rsq_f32_e32 v85, v85
	s_nop 0
	v_mul_f32_e32 v110, 0x45800000, v85
	v_cndmask_b32_e32 v110, v85, v110, vcc
	v_pk_mul_f32 v[86:87], v[86:87], v[110:111] op_sel_hi:[1,0]
	v_pk_mul_f32 v[88:89], v[88:89], v[110:111] op_sel_hi:[1,0]
	v_pk_fma_f32 v[86:87], v[0:1], v[86:87], v[8:9]
	v_pk_fma_f32 v[88:89], v[2:3], v[88:89], v[10:11]
	v_pk_mul_f32 v[100:101], v[100:101], v[110:111] op_sel_hi:[1,0]
	v_pk_mul_f32 v[90:91], v[90:91], v[110:111] op_sel_hi:[1,0]
	global_store_dwordx4 v[120:121], v[86:89], off nt
	v_pk_mul_f32 v[104:105], v[104:105], v[110:111] op_sel_hi:[1,0]
	v_pk_mul_f32 v[112:113], v[102:103], v[110:111] op_sel_hi:[1,0]
	v_pk_fma_f32 v[86:87], v[66:67], v[86:87], v[36:37]
	v_pk_fma_f32 v[102:103], v[6:7], v[90:91], v[14:15]
	v_pk_fma_f32 v[100:101], v[4:5], v[100:101], v[12:13]
	v_pk_fma_f32 v[88:89], v[64:65], v[88:89], v[38:39]
	v_cvt_pk_bf16_f32 v86, v86, v87
	v_pk_mul_f32 v[108:109], v[108:109], v[110:111] op_sel_hi:[1,0]
	v_cvt_pk_bf16_f32 v87, v88, v89
	v_pk_mul_f32 v[110:111], v[106:107], v[110:111] op_sel_hi:[1,0]
	v_pk_fma_f32 v[106:107], v[18:19], v[112:113], v[26:27]
	v_pk_fma_f32 v[104:105], v[16:17], v[104:105], v[24:25]
	v_pk_fma_f32 v[90:91], v[68:69], v[102:103], v[46:47]
	v_pk_fma_f32 v[112:113], v[70:71], v[100:101], v[44:45]
	global_store_dwordx2 v[92:93], v[86:87], off
	global_store_dwordx4 v[120:121], v[100:103], off offset:1024 nt
	v_cvt_pk_bf16_f32 v86, v112, v113
	v_cvt_pk_bf16_f32 v87, v90, v91
	v_pk_fma_f32 v[110:111], v[22:23], v[110:111], v[30:31]
	v_pk_fma_f32 v[108:109], v[20:21], v[108:109], v[28:29]
	v_pk_fma_f32 v[114:115], v[72:73], v[106:107], v[54:55]
	v_pk_fma_f32 v[116:117], v[74:75], v[104:105], v[52:53]
	global_store_dwordx2 v[92:93], v[86:87], off offset:512
	global_store_dwordx4 v[120:121], v[104:107], off offset:2048 nt
	v_cvt_pk_bf16_f32 v86, v116, v117
	v_cvt_pk_bf16_f32 v87, v114, v115
	v_pk_fma_f32 v[118:119], v[76:77], v[110:111], v[62:63]
	v_pk_fma_f32 v[122:123], v[78:79], v[108:109], v[60:61]
	global_store_dwordx2 v[92:93], v[86:87], off offset:1024
	global_store_dwordx4 v[120:121], v[108:111], off offset:3072 nt
	v_cvt_pk_bf16_f32 v86, v122, v123
	v_cvt_pk_bf16_f32 v87, v118, v119
	global_store_dwordx2 v[92:93], v[86:87], off offset:1536
	s_andn2_b64 exec, exec, s[8:9]
	s_cbranch_execnz .LBB0_1010

; DI unsigned cvt_pk_bf16(float lo, float hi) { unsigned r; asm volatile("v_cvt_pk_bf16_f32 %0, %1, %2" : "=v"(r) : "v"(lo), "v"(hi)); return r; }
; DI void convert_wt(const float* __restrict__ W, bf16_t* __restrict__ Wt, int K, int N, float* tl) {
;     ...
;     for (int tile = blockIdx.x; tile < ntiles; tile += gridDim.x) {
;         const int k0 = (tile / ntn) * 64, n0 = (tile % ntn) * 64, tj = tid & 63, ti = tid >> 6;
; #pragma unroll
;         for (int ii = 0; ii < 8; ++ii) { const int k = ti * 8 + ii; tl[k * 65 + tj] = W[(size_t)(k0 + k) * N + n0 + tj]; }
;         __syncthreads();
;         const int n = tid >> 3, ks = (tid & 7) * 8;
;         u32x4 w;
;         w[0] = cvt_pk_bf16(tl[(ks + 0) * 65 + n], tl[(ks + 1) * 65 + n]); w[1] = cvt_pk_bf16(tl[(ks + 2) * 65 + n], tl[(ks + 3) * 65 + n]);
;         w[2] = cvt_pk_bf16(tl[(ks + 4) * 65 + n], tl[(ks + 5) * 65 + n]); w[3] = cvt_pk_bf16(tl[(ks + 6) * 65 + n], tl[(ks + 7) * 65 + n]);
;         *(u32x4*)(Wt + (size_t)(n0 + n) * K + k0 + ks) = w;
;         __syncthreads();
;     }
.LBB0_1014:
	s_mul_hi_i32 s4, s10, 0x66666667
	s_lshr_b32 s5, s4, 31
	s_ashr_i32 s4, s4, 4
	s_add_i32 s5, s4, s5
	s_lshl_b32 s4, s5, 6
	s_mulk_i32 s5, 0xf600
	s_add_i32 s6, s9, s5
	s_ashr_i32 s7, s6, 31
	v_lshl_add_u64 v[14:15], s[6:7], 2, v[0:1]
	s_waitcnt vmcnt(3)
	v_add_u32_e32 v20, s4, v3
	v_mad_i64_i32 v[20:21], s[12:13], v20, s11, v[14:15]
	global_load_dword v36, v[20:21], off nt
	v_add_u32_e32 v22, s4, v5
	v_mad_i64_i32 v[22:23], s[12:13], v22, s11, v[14:15]
	global_load_dword v37, v[22:23], off nt
	s_ashr_i32 s5, s4, 31
	s_add_i32 s10, s10, s30
	s_add_i32 s9, s9, s8
	s_cmpk_lt_i32 s10, 0x280
	v_add_u32_e32 v24, s4, v6
	v_mad_i64_i32 v[24:25], s[12:13], v24, s11, v[14:15]
	global_load_dword v38, v[24:25], off nt
	v_add_u32_e32 v26, s4, v7
	v_mad_i64_i32 v[26:27], s[12:13], v26, s11, v[14:15]
	global_load_dword v39, v[26:27], off nt
	v_add_u32_e32 v28, s4, v8
	v_mad_i64_i32 v[28:29], s[12:13], v28, s11, v[14:15]
	global_load_dword v40, v[28:29], off nt
	v_add_u32_e32 v30, s4, v9
	v_mad_i64_i32 v[30:31], s[12:13], v30, s11, v[14:15]
	global_load_dword v41, v[30:31], off nt
	v_add_u32_e32 v17, 0x400, v12
	v_add_u32_e32 v32, s4, v10
	v_mad_i64_i32 v[32:33], s[12:13], v32, s11, v[14:15]
	global_load_dword v42, v[32:33], off nt
	v_add_u32_e32 v18, 0x400, v4
	v_add_u32_e32 v34, s4, v11
	v_mad_i64_i32 v[34:35], s[12:13], v34, s11, v[14:15]
	global_load_dword v43, v[34:35], off nt
	s_waitcnt vmcnt(6)
	ds_write2_b32 v12, v36, v37 offset1:65
	s_waitcnt vmcnt(4)
	ds_write2_b32 v12, v38, v39 offset0:130 offset1:195
	s_waitcnt vmcnt(2)
	ds_write2_b32 v17, v40, v41 offset0:4 offset1:69
	s_waitcnt vmcnt(1)
	ds_write_b32 v12, v42 offset:1560
	s_waitcnt vmcnt(0)
	ds_write_b32 v13, v43
	s_waitcnt lgkmcnt(0)
	s_barrier
	ds_read2_b32 v[14:15], v4 offset1:65
	s_waitcnt lgkmcnt(0)
	v_cvt_pk_bf16_f32 v14, v14, v15
	ds_read2_b32 v[16:17], v4 offset0:130 offset1:195
	s_waitcnt lgkmcnt(0)
	v_cvt_pk_bf16_f32 v15, v16, v17
	ds_read2_b32 v[16:17], v18 offset0:4 offset1:69
	s_waitcnt lgkmcnt(0)
	v_cvt_pk_bf16_f32 v16, v16, v17
	ds_read2_b32 v[18:19], v18 offset0:134 offset1:199
	s_waitcnt lgkmcnt(0)
	v_cvt_pk_bf16_f32 v17, v18, v19
	v_add_u32_e32 v18, s6, v2
	v_ashrrev_i32_e32 v19, 31, v18
	v_lshlrev_b64 v[18:19], 11, v[18:19]
	v_lshl_add_u64 v[18:19], s[28:29], 0, v[18:19]
	v_lshl_add_u64 v[18:19], s[4:5], 1, v[18:19]
	v_lshl_add_u64 v[18:19], v[18:19], 0, v[180:181]
	global_store_dwordx4 v[18:19], v[14:17], off
	s_barrier
	s_cbranch_scc1 .LBB0_1014

; DI unsigned cvt_pk_bf16(float lo, float hi) { unsigned r; asm volatile("v_cvt_pk_bf16_f32 %0, %1, %2" : "=v"(r) : "v"(lo), "v"(hi)); return r; }
; DI void convert_wt(const float* __restrict__ W, bf16_t* __restrict__ Wt, int K, int N, float* tl) {
;     ...
;     for (int tile = blockIdx.x; tile < ntiles; tile += gridDim.x) {
;         const int k0 = (tile / ntn) * 64, n0 = (tile % ntn) * 64, tj = tid & 63, ti = tid >> 6;
; #pragma unroll
;         for (int ii = 0; ii < 8; ++ii) { const int k = ti * 8 + ii; tl[k * 65 + tj] = W[(size_t)(k0 + k) * N + n0 + tj]; }
;         __syncthreads();
;         const int n = tid >> 3, ks = (tid & 7) * 8;
;         u32x4 w;
;         w[0] = cvt_pk_bf16(tl[(ks + 0) * 65 + n], tl[(ks + 1) * 65 + n]); w[1] = cvt_pk_bf16(tl[(ks + 2) * 65 + n], tl[(ks + 3) * 65 + n]);
;         w[2] = cvt_pk_bf16(tl[(ks + 4) * 65 + n], tl[(ks + 5) * 65 + n]); w[3] = cvt_pk_bf16(tl[(ks + 6) * 65 + n], tl[(ks + 7) * 65 + n]);
;         *(u32x4*)(Wt + (size_t)(n0 + n) * K + k0 + ks) = w;
;         __syncthreads();
;     }
.LBB0_1017:
	s_ashr_i32 s4, s10, 31
	s_lshr_b32 s4, s4, 28
	s_add_i32 s4, s10, s4
	s_ashr_i32 s5, s4, 4
	s_lshl_b32 s4, s5, 6
	s_lshl_b32 s5, s5, 10
	s_sub_i32 s6, s9, s5
	s_waitcnt vmcnt(3)
	s_ashr_i32 s7, s6, 31
	v_lshl_add_u64 v[2:3], s[6:7], 2, v[0:1]
	v_add_u32_e32 v20, s4, v5
	v_ashrrev_i32_e32 v21, 31, v20
	v_lshlrev_b64 v[20:21], 12, v[20:21]
	v_lshl_add_u64 v[20:21], v[2:3], 0, v[20:21]
	global_load_dword v36, v[20:21], off nt
	v_add_u32_e32 v22, s4, v7
	v_ashrrev_i32_e32 v23, 31, v22
	v_lshlrev_b64 v[22:23], 12, v[22:23]
	v_lshl_add_u64 v[22:23], v[2:3], 0, v[22:23]
	global_load_dword v37, v[22:23], off nt
	v_add_u32_e32 v19, 0x400, v6
	s_ashr_i32 s5, s4, 31
	s_add_i32 s10, s10, s30
	s_add_i32 s9, s9, s8
	s_cmpk_gt_i32 s10, 0xff
	v_add_u32_e32 v24, s4, v8
	v_ashrrev_i32_e32 v25, 31, v24
	v_lshlrev_b64 v[24:25], 12, v[24:25]
	v_lshl_add_u64 v[24:25], v[2:3], 0, v[24:25]
	global_load_dword v38, v[24:25], off nt
	v_add_u32_e32 v26, s4, v9
	v_ashrrev_i32_e32 v27, 31, v26
	v_lshlrev_b64 v[26:27], 12, v[26:27]
	v_lshl_add_u64 v[26:27], v[2:3], 0, v[26:27]
	global_load_dword v39, v[26:27], off nt
	v_add_u32_e32 v28, s4, v10
	v_ashrrev_i32_e32 v29, 31, v28
	v_lshlrev_b64 v[28:29], 12, v[28:29]
	v_lshl_add_u64 v[28:29], v[2:3], 0, v[28:29]
	global_load_dword v40, v[28:29], off nt
	v_add_u32_e32 v30, s4, v11
	v_ashrrev_i32_e32 v31, 31, v30
	v_lshlrev_b64 v[30:31], 12, v[30:31]
	v_lshl_add_u64 v[30:31], v[2:3], 0, v[30:31]
	global_load_dword v41, v[30:31], off nt
	v_add_u32_e32 v17, 0x400, v14
	v_add_u32_e32 v32, s4, v12
	v_ashrrev_i32_e32 v33, 31, v32
	v_lshlrev_b64 v[32:33], 12, v[32:33]
	v_lshl_add_u64 v[32:33], v[2:3], 0, v[32:33]
	global_load_dword v42, v[32:33], off nt
	v_add_u32_e32 v34, s4, v13
	v_ashrrev_i32_e32 v35, 31, v34
	v_lshlrev_b64 v[34:35], 12, v[34:35]
	v_lshl_add_u64 v[34:35], v[2:3], 0, v[34:35]
	global_load_dword v43, v[34:35], off nt
	s_waitcnt vmcnt(6)
	ds_write2_b32 v14, v36, v37 offset1:65
	s_waitcnt vmcnt(4)
	ds_write2_b32 v14, v38, v39 offset0:130 offset1:195
	s_waitcnt vmcnt(2)
	ds_write2_b32 v17, v40, v41 offset0:4 offset1:69
	s_waitcnt vmcnt(1)
	ds_write_b32 v14, v42 offset:1560
	s_waitcnt vmcnt(0)
	ds_write_b32 v15, v43
	s_waitcnt lgkmcnt(0)
	s_barrier
	ds_read2_b32 v[2:3], v6 offset1:65
	s_waitcnt lgkmcnt(0)
	v_cvt_pk_bf16_f32 v16, v2, v3
	ds_read2_b32 v[2:3], v6 offset0:130 offset1:195
	s_waitcnt lgkmcnt(0)
	v_cvt_pk_bf16_f32 v17, v2, v3
	ds_read2_b32 v[2:3], v19 offset0:4 offset1:69
	s_waitcnt lgkmcnt(0)
	v_cvt_pk_bf16_f32 v18, v2, v3
	ds_read2_b32 v[2:3], v19 offset0:134 offset1:199
	s_waitcnt lgkmcnt(0)
	v_cvt_pk_bf16_f32 v19, v2, v3
	v_add_u32_e32 v2, s6, v4
	v_ashrrev_i32_e32 v3, 31, v2
	v_lshlrev_b64 v[2:3], 11, v[2:3]
	v_lshl_add_u64 v[2:3], s[54:55], 0, v[2:3]
	v_lshl_add_u64 v[2:3], s[4:5], 1, v[2:3]
	v_lshl_add_u64 v[2:3], v[2:3], 0, v[180:181]
	global_store_dwordx4 v[2:3], v[16:19], off
	s_barrier
	s_cbranch_scc0 .LBB0_1017

; DI int opq_tid() { int t = threadIdx.x; asm volatile("" : "+v"(t)); return t; }
; DI unsigned cvt_pk_bf16(float lo, float hi) { unsigned r; asm volatile("v_cvt_pk_bf16_f32 %0, %1, %2" : "=v"(r) : "v"(lo), "v"(hi)); return r; }
; DI void convert_wt(const float* __restrict__ W, bf16_t* __restrict__ Wt, int K, int N, float* tl) {
;     const int tid = opq_tid(), ntn = N / 64, ntiles = (K / 64) * ntn;
;     for (int tile = blockIdx.x; tile < ntiles; tile += gridDim.x) {
;         const int k0 = (tile / ntn) * 64, n0 = (tile % ntn) * 64, tj = tid & 63, ti = tid >> 6;
; #pragma unroll
;         for (int ii = 0; ii < 8; ++ii) { const int k = ti * 8 + ii; tl[k * 65 + tj] = W[(size_t)(k0 + k) * N + n0 + tj]; }
;         __syncthreads();
;         const int n = tid >> 3, ks = (tid & 7) * 8;
;         u32x4 w;
;         w[0] = cvt_pk_bf16(tl[(ks + 0) * 65 + n], tl[(ks + 1) * 65 + n]); w[1] = cvt_pk_bf16(tl[(ks + 2) * 65 + n], tl[(ks + 3) * 65 + n]);
;         w[2] = cvt_pk_bf16(tl[(ks + 4) * 65 + n], tl[(ks + 5) * 65 + n]); w[3] = cvt_pk_bf16(tl[(ks + 6) * 65 + n], tl[(ks + 7) * 65 + n]);
;         *(u32x4*)(Wt + (size_t)(n0 + n) * K + k0 + ks) = w;
;         __syncthreads();
;     }
; }
.LBB0_1022:
	s_mul_hi_i32 s4, s10, 0x2aaaaaab
	s_lshr_b32 s5, s4, 31
	s_ashr_i32 s4, s4, 4
	s_add_i32 s5, s4, s5
	s_lshl_b32 s4, s5, 6
	s_mulk_i32 s5, 0xe800
	s_add_i32 s6, s9, s5
	s_ashr_i32 s7, s6, 31
	v_lshl_add_u64 v[14:15], s[6:7], 2, v[0:1]
	s_waitcnt vmcnt(3)
	v_add_u32_e32 v20, s4, v3
	v_mad_i64_i32 v[20:21], s[12:13], v20, s11, v[14:15]
	global_load_dword v36, v[20:21], off nt
	v_add_u32_e32 v22, s4, v5
	v_mad_i64_i32 v[22:23], s[12:13], v22, s11, v[14:15]
	global_load_dword v37, v[22:23], off nt
	s_ashr_i32 s5, s4, 31
	s_add_i32 s10, s10, s30
	s_add_i32 s9, s9, s8
	s_cmpk_lt_i32 s10, 0x600
	v_add_u32_e32 v24, s4, v6
	v_mad_i64_i32 v[24:25], s[12:13], v24, s11, v[14:15]
	global_load_dword v38, v[24:25], off nt
	v_add_u32_e32 v26, s4, v7
	v_mad_i64_i32 v[26:27], s[12:13], v26, s11, v[14:15]
	global_load_dword v39, v[26:27], off nt
	v_add_u32_e32 v28, s4, v8
	v_mad_i64_i32 v[28:29], s[12:13], v28, s11, v[14:15]
	global_load_dword v40, v[28:29], off nt
	v_add_u32_e32 v30, s4, v9
	v_mad_i64_i32 v[30:31], s[12:13], v30, s11, v[14:15]
	global_load_dword v41, v[30:31], off nt
	v_add_u32_e32 v17, 0x400, v12
	v_add_u32_e32 v32, s4, v10
	v_mad_i64_i32 v[32:33], s[12:13], v32, s11, v[14:15]
	global_load_dword v42, v[32:33], off nt
	v_add_u32_e32 v18, 0x400, v4
	v_add_u32_e32 v34, s4, v11
	v_mad_i64_i32 v[34:35], s[12:13], v34, s11, v[14:15]
	global_load_dword v43, v[34:35], off nt
	s_waitcnt vmcnt(6)
	ds_write2_b32 v12, v36, v37 offset1:65
	s_waitcnt vmcnt(4)
	ds_write2_b32 v12, v38, v39 offset0:130 offset1:195
	s_waitcnt vmcnt(2)
	ds_write2_b32 v17, v40, v41 offset0:4 offset1:69
	s_waitcnt vmcnt(1)
	ds_write_b32 v12, v42 offset:1560
	s_waitcnt vmcnt(0)
	ds_write_b32 v13, v43
	s_waitcnt lgkmcnt(0)
	s_barrier
	ds_read2_b32 v[14:15], v4 offset1:65
	s_waitcnt lgkmcnt(0)
	v_cvt_pk_bf16_f32 v14, v14, v15
	ds_read2_b32 v[16:17], v4 offset0:130 offset1:195
	s_waitcnt lgkmcnt(0)
	v_cvt_pk_bf16_f32 v15, v16, v17
	ds_read2_b32 v[16:17], v18 offset0:4 offset1:69
	s_waitcnt lgkmcnt(0)
	v_cvt_pk_bf16_f32 v16, v16, v17
	ds_read2_b32 v[18:19], v18 offset0:134 offset1:199
	s_waitcnt lgkmcnt(0)
	v_cvt_pk_bf16_f32 v17, v18, v19
	v_add_u32_e32 v18, s6, v2
	v_ashrrev_i32_e32 v19, 31, v18
	v_lshlrev_b64 v[18:19], 11, v[18:19]
	v_lshl_add_u64 v[18:19], s[28:29], 0, v[18:19]
	v_lshl_add_u64 v[18:19], s[4:5], 1, v[18:19]
	v_lshl_add_u64 v[18:19], v[18:19], 0, v[180:181]
	global_store_dwordx4 v[18:19], v[14:17], off
	s_barrier
	s_cbranch_scc1 .LBB0_1022

; DI int opq_tid() { int t = threadIdx.x; asm volatile("" : "+v"(t)); return t; }
; DI unsigned cvt_pk_bf16(float lo, float hi) { unsigned r; asm volatile("v_cvt_pk_bf16_f32 %0, %1, %2" : "=v"(r) : "v"(lo), "v"(hi)); return r; }
; DI void convert_wt(const float* __restrict__ W, bf16_t* __restrict__ Wt, int K, int N, float* tl) {
;     const int tid = opq_tid(), ntn = N / 64, ntiles = (K / 64) * ntn;
;     for (int tile = blockIdx.x; tile < ntiles; tile += gridDim.x) {
;         const int k0 = (tile / ntn) * 64, n0 = (tile % ntn) * 64, tj = tid & 63, ti = tid >> 6;
; #pragma unroll
;         for (int ii = 0; ii < 8; ++ii) { const int k = ti * 8 + ii; tl[k * 65 + tj] = W[(size_t)(k0 + k) * N + n0 + tj]; }
;         __syncthreads();
;         const int n = tid >> 3, ks = (tid & 7) * 8;
;         u32x4 w;
;         w[0] = cvt_pk_bf16(tl[(ks + 0) * 65 + n], tl[(ks + 1) * 65 + n]); w[1] = cvt_pk_bf16(tl[(ks + 2) * 65 + n], tl[(ks + 3) * 65 + n]);
;         w[2] = cvt_pk_bf16(tl[(ks + 4) * 65 + n], tl[(ks + 5) * 65 + n]); w[3] = cvt_pk_bf16(tl[(ks + 6) * 65 + n], tl[(ks + 7) * 65 + n]);
;         *(u32x4*)(Wt + (size_t)(n0 + n) * K + k0 + ks) = w;
;         __syncthreads();
;     }
; }
.LBB0_1025:
	s_ashr_i32 s0, s8, 31
	s_lshr_b32 s0, s0, 28
	s_add_i32 s0, s8, s0
	s_ashr_i32 s1, s0, 4
	s_lshl_b32 s0, s1, 6
	s_lshl_b32 s1, s1, 10
	s_sub_i32 s4, s7, s1
	s_waitcnt vmcnt(3)
	s_ashr_i32 s5, s4, 31
	v_lshl_add_u64 v[2:3], s[4:5], 2, v[0:1]
	v_add_u32_e32 v20, s0, v5
	v_ashrrev_i32_e32 v21, 31, v20
	v_lshlrev_b64 v[20:21], 12, v[20:21]
	v_lshl_add_u64 v[20:21], v[2:3], 0, v[20:21]
	global_load_dword v36, v[20:21], off nt
	v_add_u32_e32 v22, s0, v7
	v_ashrrev_i32_e32 v23, 31, v22
	v_lshlrev_b64 v[22:23], 12, v[22:23]
	v_lshl_add_u64 v[22:23], v[2:3], 0, v[22:23]
	global_load_dword v37, v[22:23], off nt
	v_add_u32_e32 v19, 0x400, v6
	s_ashr_i32 s1, s0, 31
	s_add_i32 s8, s8, s30
	s_add_i32 s7, s7, s6
	s_cmpk_gt_i32 s8, 0x1ff
	v_add_u32_e32 v24, s0, v8
	v_ashrrev_i32_e32 v25, 31, v24
	v_lshlrev_b64 v[24:25], 12, v[24:25]
	v_lshl_add_u64 v[24:25], v[2:3], 0, v[24:25]
	global_load_dword v38, v[24:25], off nt
	v_add_u32_e32 v26, s0, v9
	v_ashrrev_i32_e32 v27, 31, v26
	v_lshlrev_b64 v[26:27], 12, v[26:27]
	v_lshl_add_u64 v[26:27], v[2:3], 0, v[26:27]
	global_load_dword v39, v[26:27], off nt
	v_add_u32_e32 v28, s0, v10
	v_ashrrev_i32_e32 v29, 31, v28
	v_lshlrev_b64 v[28:29], 12, v[28:29]
	v_lshl_add_u64 v[28:29], v[2:3], 0, v[28:29]
	global_load_dword v40, v[28:29], off nt
	v_add_u32_e32 v30, s0, v11
	v_ashrrev_i32_e32 v31, 31, v30
	v_lshlrev_b64 v[30:31], 12, v[30:31]
	v_lshl_add_u64 v[30:31], v[2:3], 0, v[30:31]
	global_load_dword v41, v[30:31], off nt
	v_add_u32_e32 v17, 0x400, v14
	v_add_u32_e32 v32, s0, v12
	v_ashrrev_i32_e32 v33, 31, v32
	v_lshlrev_b64 v[32:33], 12, v[32:33]
	v_lshl_add_u64 v[32:33], v[2:3], 0, v[32:33]
	global_load_dword v42, v[32:33], off nt
	v_add_u32_e32 v34, s0, v13
	v_ashrrev_i32_e32 v35, 31, v34
	v_lshlrev_b64 v[34:35], 12, v[34:35]
	v_lshl_add_u64 v[34:35], v[2:3], 0, v[34:35]
	global_load_dword v43, v[34:35], off nt
	s_waitcnt vmcnt(6)
	ds_write2_b32 v14, v36, v37 offset1:65
	s_waitcnt vmcnt(4)
	ds_write2_b32 v14, v38, v39 offset0:130 offset1:195
	s_waitcnt vmcnt(2)
	ds_write2_b32 v17, v40, v41 offset0:4 offset1:69
	s_waitcnt vmcnt(1)
	ds_write_b32 v14, v42 offset:1560
	s_waitcnt vmcnt(0)
	ds_write_b32 v15, v43
	s_waitcnt lgkmcnt(0)
	s_barrier
	ds_read2_b32 v[2:3], v6 offset1:65
	s_waitcnt lgkmcnt(0)
	v_cvt_pk_bf16_f32 v16, v2, v3
	ds_read2_b32 v[2:3], v6 offset0:130 offset1:195
	s_waitcnt lgkmcnt(0)
	v_cvt_pk_bf16_f32 v17, v2, v3
	ds_read2_b32 v[2:3], v19 offset0:4 offset1:69
	s_waitcnt lgkmcnt(0)
	v_cvt_pk_bf16_f32 v18, v2, v3
	ds_read2_b32 v[2:3], v19 offset0:134 offset1:199
	s_waitcnt lgkmcnt(0)
	v_cvt_pk_bf16_f32 v19, v2, v3
	v_add_u32_e32 v2, s4, v4
	v_ashrrev_i32_e32 v3, 31, v2
	v_lshlrev_b64 v[2:3], 12, v[2:3]
	v_lshl_add_u64 v[2:3], s[20:21], 0, v[2:3]
	v_lshl_add_u64 v[2:3], s[0:1], 1, v[2:3]
	v_lshl_add_u64 v[2:3], v[2:3], 0, v[180:181]
	global_store_dwordx4 v[2:3], v[16:19], off
	s_barrier
	s_cbranch_scc0 .LBB0_1025
